# v32 + K-loop LDS-DMA loads in scalar-base form (no VALU address adds in the load segments; 74 v_lshl_add_u64 removed from the five K-loops)
# speedup vs baseline: 1.0074x; 1.0012x over previous
.LBB0_228:
	ds_read_b128 v[128:131], v179
	ds_read_b128 v[132:135], v179 offset:1024
	ds_read_b128 v[136:139], v179 offset:2048
	ds_read_b128 v[140:143], v179 offset:3072
	ds_read_b128 v[162:165], v180
	ds_read_b128 v[166:169], v180 offset:1024
	ds_read_b128 v[170:173], v180 offset:2048
	ds_read_b128 v[186:189], v180 offset:3072
	s_add_u32 s8, s6, 0x10000
	s_addc_u32 s9, s7, 0
	s_cmp_eq_u32 s92, 12
	s_cselect_b32 s80, s69, s8
	s_cselect_b32 s81, s18, s9
	s_cselect_b32 s12, s77, vcc_lo
	s_cselect_b32 s13, s71, vcc_hi
	s_add_u32 s10, s80, 0x8000
	s_addc_u32 s11, s81, 0
	s_add_i32 m0, s79, 0xc000
	ds_read_b128 v[190:193], v181
	ds_read_b128 v[194:197], v181 offset:1024
	ds_read_b128 v[198:201], v181 offset:2048
	ds_read_b128 v[202:205], v181 offset:3072
	ds_read_b128 v[206:209], v181 offset:4096
	ds_read_b128 v[210:213], v181 offset:5120
	ds_read_b128 v[214:217], v181 offset:6144
	ds_read_b128 v[218:221], v181 offset:7168
	global_load_lds_dwordx4 v154, s[6:7]
	s_add_i32 m0, s79, 0xe000
	s_nop 0
	global_load_lds_dwordx4 v156, s[6:7]
	s_waitcnt vmcnt(8)
	s_waitcnt lgkmcnt(0)
	s_barrier
	s_setprio 1
	s_waitcnt lgkmcnt(0)
	v_mfma_f32_16x16x32_bf16 v[124:127], v[128:131], v[190:193], v[124:127]
	v_mfma_f32_16x16x32_bf16 v[120:123], v[136:139], v[190:193], v[120:123]
	v_mfma_f32_16x16x32_bf16 v[108:111], v[128:131], v[198:201], v[108:111]
	v_mfma_f32_16x16x32_bf16 v[104:107], v[136:139], v[198:201], v[104:107]
	v_mfma_f32_16x16x32_bf16 v[92:95], v[128:131], v[206:209], v[92:95]
	v_mfma_f32_16x16x32_bf16 v[88:91], v[136:139], v[206:209], v[88:91]
	v_mfma_f32_16x16x32_bf16 v[76:79], v[128:131], v[214:217], v[76:79]
	v_mfma_f32_16x16x32_bf16 v[72:75], v[136:139], v[214:217], v[72:75]
	v_mfma_f32_16x16x32_bf16 v[124:127], v[132:135], v[194:197], v[124:127]
	v_mfma_f32_16x16x32_bf16 v[120:123], v[140:143], v[194:197], v[120:123]
	v_mfma_f32_16x16x32_bf16 v[108:111], v[132:135], v[202:205], v[108:111]
	v_mfma_f32_16x16x32_bf16 v[104:107], v[140:143], v[202:205], v[104:107]
	v_mfma_f32_16x16x32_bf16 v[92:95], v[132:135], v[210:213], v[92:95]
	v_mfma_f32_16x16x32_bf16 v[88:91], v[140:143], v[210:213], v[88:91]
	v_mfma_f32_16x16x32_bf16 v[76:79], v[132:135], v[218:221], v[76:79]
	v_mfma_f32_16x16x32_bf16 v[72:75], v[140:143], v[218:221], v[72:75]
	s_setprio 0
	s_setprio 1
	v_mfma_f32_16x16x32_bf16 v[116:119], v[162:165], v[190:193], v[116:119]
	v_mfma_f32_16x16x32_bf16 v[112:115], v[170:173], v[190:193], v[112:115]
	v_mfma_f32_16x16x32_bf16 v[100:103], v[162:165], v[198:201], v[100:103]
	v_mfma_f32_16x16x32_bf16 v[96:99], v[170:173], v[198:201], v[96:99]
	v_mfma_f32_16x16x32_bf16 v[84:87], v[162:165], v[206:209], v[84:87]
	v_mfma_f32_16x16x32_bf16 v[80:83], v[170:173], v[206:209], v[80:83]
	v_mfma_f32_16x16x32_bf16 v[68:71], v[162:165], v[214:217], v[68:71]
	v_mfma_f32_16x16x32_bf16 v[64:67], v[170:173], v[214:217], v[64:67]
	v_mfma_f32_16x16x32_bf16 v[116:119], v[166:169], v[194:197], v[116:119]
	v_mfma_f32_16x16x32_bf16 v[112:115], v[186:189], v[194:197], v[112:115]
	v_mfma_f32_16x16x32_bf16 v[100:103], v[166:169], v[202:205], v[100:103]
	v_mfma_f32_16x16x32_bf16 v[96:99], v[186:189], v[202:205], v[96:99]
	v_mfma_f32_16x16x32_bf16 v[84:87], v[166:169], v[210:213], v[84:87]
	v_mfma_f32_16x16x32_bf16 v[80:83], v[186:189], v[210:213], v[80:83]
	v_mfma_f32_16x16x32_bf16 v[68:71], v[166:169], v[218:221], v[68:71]
	v_mfma_f32_16x16x32_bf16 v[64:67], v[186:189], v[218:221], v[64:67]
	s_setprio 0
	s_barrier
	s_add_i32 s6, s34, s84
	s_mov_b32 m0, s6
	ds_read_b128 v[190:193], v181 offset:16384
	ds_read_b128 v[194:197], v181 offset:17408
	ds_read_b128 v[198:201], v181 offset:18432
	ds_read_b128 v[202:205], v181 offset:19456
	ds_read_b128 v[206:209], v181 offset:20480
	ds_read_b128 v[210:213], v181 offset:21504
	ds_read_b128 v[214:217], v181 offset:22528
	ds_read_b128 v[218:221], v181 offset:23552
	global_load_lds_dwordx4 v146, s[12:13]
	s_add_i32 m0, s6, 0x2000
	s_add_u32 s6, s12, 0x40000
	s_addc_u32 s7, s13, 0
	s_add_i32 s38, s35, s84
	global_load_lds_dwordx4 v150, s[12:13]
	s_mov_b32 m0, s38
	s_nop 0
	global_load_lds_dwordx4 v146, s[6:7]
	s_add_i32 m0, s38, 0x2000
	s_nop 0
	global_load_lds_dwordx4 v150, s[6:7]
	s_mov_b32 m0, s79
	s_nop 0
	global_load_lds_dwordx4 v144, s[80:81]
	s_mov_b32 m0, s85
	s_nop 0
	global_load_lds_dwordx4 v148, s[80:81]
	s_waitcnt vmcnt(8)
	s_waitcnt lgkmcnt(0)
	s_barrier
	s_setprio 1
	s_waitcnt lgkmcnt(0)
	v_mfma_f32_16x16x32_bf16 v[60:63], v[128:131], v[190:193], v[60:63]
	v_mfma_f32_16x16x32_bf16 v[56:59], v[136:139], v[190:193], v[56:59]
	v_mfma_f32_16x16x32_bf16 v[44:47], v[128:131], v[198:201], v[44:47]
	v_mfma_f32_16x16x32_bf16 v[40:43], v[136:139], v[198:201], v[40:43]
	v_mfma_f32_16x16x32_bf16 v[28:31], v[128:131], v[206:209], v[28:31]
	v_mfma_f32_16x16x32_bf16 v[24:27], v[136:139], v[206:209], v[24:27]
	v_mfma_f32_16x16x32_bf16 v[12:15], v[128:131], v[214:217], v[12:15]
	v_mfma_f32_16x16x32_bf16 v[8:11], v[136:139], v[214:217], v[8:11]
	v_mfma_f32_16x16x32_bf16 v[60:63], v[132:135], v[194:197], v[60:63]
	v_mfma_f32_16x16x32_bf16 v[56:59], v[140:143], v[194:197], v[56:59]
	v_mfma_f32_16x16x32_bf16 v[44:47], v[132:135], v[202:205], v[44:47]
	v_mfma_f32_16x16x32_bf16 v[40:43], v[140:143], v[202:205], v[40:43]
	v_mfma_f32_16x16x32_bf16 v[28:31], v[132:135], v[210:213], v[28:31]
	v_mfma_f32_16x16x32_bf16 v[24:27], v[140:143], v[210:213], v[24:27]
	v_mfma_f32_16x16x32_bf16 v[12:15], v[132:135], v[218:221], v[12:15]
	v_mfma_f32_16x16x32_bf16 v[8:11], v[140:143], v[218:221], v[8:11]
	s_setprio 0
	s_setprio 1
	v_mfma_f32_16x16x32_bf16 v[52:55], v[162:165], v[190:193], v[52:55]
	v_mfma_f32_16x16x32_bf16 v[48:51], v[170:173], v[190:193], v[48:51]
	v_mfma_f32_16x16x32_bf16 v[36:39], v[162:165], v[198:201], v[36:39]
	v_mfma_f32_16x16x32_bf16 v[32:35], v[170:173], v[198:201], v[32:35]
	v_mfma_f32_16x16x32_bf16 v[20:23], v[162:165], v[206:209], v[20:23]
	v_mfma_f32_16x16x32_bf16 v[16:19], v[170:173], v[206:209], v[16:19]
	v_mfma_f32_16x16x32_bf16 v[4:7], v[162:165], v[214:217], v[4:7]
	v_mfma_f32_16x16x32_bf16 v[0:3], v[170:173], v[214:217], v[0:3]
	v_mfma_f32_16x16x32_bf16 v[52:55], v[166:169], v[194:197], v[52:55]
	v_mfma_f32_16x16x32_bf16 v[48:51], v[186:189], v[194:197], v[48:51]
	v_mfma_f32_16x16x32_bf16 v[36:39], v[166:169], v[202:205], v[36:39]
	v_mfma_f32_16x16x32_bf16 v[32:35], v[186:189], v[202:205], v[32:35]
	v_mfma_f32_16x16x32_bf16 v[20:23], v[166:169], v[210:213], v[20:23]
	v_mfma_f32_16x16x32_bf16 v[16:19], v[186:189], v[210:213], v[16:19]
	v_mfma_f32_16x16x32_bf16 v[4:7], v[166:169], v[218:221], v[4:7]
	v_mfma_f32_16x16x32_bf16 v[0:3], v[186:189], v[218:221], v[0:3]
	s_setprio 0
	s_barrier
	s_add_i32 s38, 0, 0x18000
	s_add_i32 s39, 0, 0x1c000
	v_add_u32_e32 v140, s38, v178
	v_add_u32_e32 v152, s39, v178
	ds_read_b128 v[128:131], v140
	ds_read_b128 v[132:135], v140 offset:1024
	ds_read_b128 v[136:139], v140 offset:2048
	ds_read_b128 v[140:143], v140 offset:3072
	ds_read_b128 v[162:165], v152
	ds_read_b128 v[166:169], v152 offset:1024
	ds_read_b128 v[170:173], v152 offset:2048
	ds_read_b128 v[186:189], v152 offset:3072
	s_add_u32 s6, s80, 0x4000
	s_addc_u32 s7, s81, 0
	s_mov_b32 m0, s86
	ds_read_b128 v[190:193], v181 offset:32768
	ds_read_b128 v[194:197], v181 offset:33792
	ds_read_b128 v[198:201], v181 offset:34816
	ds_read_b128 v[202:205], v181 offset:35840
	ds_read_b128 v[206:209], v181 offset:36864
	ds_read_b128 v[210:213], v181 offset:37888
	ds_read_b128 v[214:217], v181 offset:38912
	ds_read_b128 v[218:221], v181 offset:39936
	global_load_lds_dwordx4 v144, s[6:7]
	s_mov_b32 m0, s87
	s_nop 0
	global_load_lds_dwordx4 v148, s[6:7]
	s_waitcnt vmcnt(8)
	s_waitcnt lgkmcnt(0)
	s_barrier
	s_setprio 1
	s_waitcnt lgkmcnt(0)
	v_mfma_f32_16x16x32_bf16 v[124:127], v[128:131], v[190:193], v[124:127]
	v_mfma_f32_16x16x32_bf16 v[120:123], v[136:139], v[190:193], v[120:123]
	v_mfma_f32_16x16x32_bf16 v[108:111], v[128:131], v[198:201], v[108:111]
	v_mfma_f32_16x16x32_bf16 v[104:107], v[136:139], v[198:201], v[104:107]
	v_mfma_f32_16x16x32_bf16 v[92:95], v[128:131], v[206:209], v[92:95]
	v_mfma_f32_16x16x32_bf16 v[88:91], v[136:139], v[206:209], v[88:91]
	v_mfma_f32_16x16x32_bf16 v[76:79], v[128:131], v[214:217], v[76:79]
	v_mfma_f32_16x16x32_bf16 v[72:75], v[136:139], v[214:217], v[72:75]
	v_mfma_f32_16x16x32_bf16 v[124:127], v[132:135], v[194:197], v[124:127]
	v_mfma_f32_16x16x32_bf16 v[120:123], v[140:143], v[194:197], v[120:123]
	v_mfma_f32_16x16x32_bf16 v[108:111], v[132:135], v[202:205], v[108:111]
	v_mfma_f32_16x16x32_bf16 v[104:107], v[140:143], v[202:205], v[104:107]
	v_mfma_f32_16x16x32_bf16 v[92:95], v[132:135], v[210:213], v[92:95]
	v_mfma_f32_16x16x32_bf16 v[88:91], v[140:143], v[210:213], v[88:91]
	v_mfma_f32_16x16x32_bf16 v[76:79], v[132:135], v[218:221], v[76:79]
	v_mfma_f32_16x16x32_bf16 v[72:75], v[140:143], v[218:221], v[72:75]
	s_setprio 0
	s_setprio 1
	v_mfma_f32_16x16x32_bf16 v[116:119], v[162:165], v[190:193], v[116:119]
	v_mfma_f32_16x16x32_bf16 v[112:115], v[170:173], v[190:193], v[112:115]
	v_mfma_f32_16x16x32_bf16 v[100:103], v[162:165], v[198:201], v[100:103]
	v_mfma_f32_16x16x32_bf16 v[96:99], v[170:173], v[198:201], v[96:99]
	v_mfma_f32_16x16x32_bf16 v[84:87], v[162:165], v[206:209], v[84:87]
	v_mfma_f32_16x16x32_bf16 v[80:83], v[170:173], v[206:209], v[80:83]
	v_mfma_f32_16x16x32_bf16 v[68:71], v[162:165], v[214:217], v[68:71]
	v_mfma_f32_16x16x32_bf16 v[64:67], v[170:173], v[214:217], v[64:67]
	v_mfma_f32_16x16x32_bf16 v[116:119], v[166:169], v[194:197], v[116:119]
	v_mfma_f32_16x16x32_bf16 v[112:115], v[186:189], v[194:197], v[112:115]
	v_mfma_f32_16x16x32_bf16 v[100:103], v[166:169], v[202:205], v[100:103]
	v_mfma_f32_16x16x32_bf16 v[96:99], v[186:189], v[202:205], v[96:99]
	v_mfma_f32_16x16x32_bf16 v[84:87], v[166:169], v[210:213], v[84:87]
	v_mfma_f32_16x16x32_bf16 v[80:83], v[186:189], v[210:213], v[80:83]
	v_mfma_f32_16x16x32_bf16 v[68:71], v[166:169], v[218:221], v[68:71]
	v_mfma_f32_16x16x32_bf16 v[64:67], v[186:189], v[218:221], v[64:67]
	s_setprio 0
	s_barrier
	s_add_u32 s98, s12, s48
	s_addc_u32 s99, s13, s49
	s_add_i32 s6, s38, s84
	s_mov_b32 m0, s6
	ds_read_b128 v[190:193], v181 offset:49152
	ds_read_b128 v[194:197], v181 offset:50176
	ds_read_b128 v[198:201], v181 offset:51200
	ds_read_b128 v[202:205], v181 offset:52224
	ds_read_b128 v[206:209], v181 offset:53248
	ds_read_b128 v[210:213], v181 offset:54272
	ds_read_b128 v[214:217], v181 offset:55296
	ds_read_b128 v[218:221], v181 offset:56320
	global_load_lds_dwordx4 v146, s[98:99]
	s_add_i32 m0, s6, 0x2000
	s_add_u32 s6, s12, 0x40080
	s_addc_u32 s7, s13, 0
	s_add_i32 s12, s39, s84
	global_load_lds_dwordx4 v150, s[98:99]
	s_mov_b32 m0, s12
	s_nop 0
	global_load_lds_dwordx4 v146, s[6:7]
	s_add_i32 m0, s12, 0x2000
	s_nop 0
	global_load_lds_dwordx4 v150, s[6:7]
	s_mov_b32 m0, s33
	s_nop 0
	global_load_lds_dwordx4 v144, s[10:11]
	s_mov_b32 m0, s56
	s_nop 0
	global_load_lds_dwordx4 v148, s[10:11]
	s_waitcnt vmcnt(8)
	s_waitcnt lgkmcnt(0)
	s_barrier
	s_setprio 1
	s_waitcnt lgkmcnt(0)
	v_mfma_f32_16x16x32_bf16 v[60:63], v[128:131], v[190:193], v[60:63]
	v_mfma_f32_16x16x32_bf16 v[56:59], v[136:139], v[190:193], v[56:59]
	v_mfma_f32_16x16x32_bf16 v[44:47], v[128:131], v[198:201], v[44:47]
	v_mfma_f32_16x16x32_bf16 v[40:43], v[136:139], v[198:201], v[40:43]
	v_mfma_f32_16x16x32_bf16 v[28:31], v[128:131], v[206:209], v[28:31]
	v_mfma_f32_16x16x32_bf16 v[24:27], v[136:139], v[206:209], v[24:27]
	v_mfma_f32_16x16x32_bf16 v[12:15], v[128:131], v[214:217], v[12:15]
	v_mfma_f32_16x16x32_bf16 v[8:11], v[136:139], v[214:217], v[8:11]
	v_mfma_f32_16x16x32_bf16 v[60:63], v[132:135], v[194:197], v[60:63]
	v_mfma_f32_16x16x32_bf16 v[56:59], v[140:143], v[194:197], v[56:59]
	v_mfma_f32_16x16x32_bf16 v[44:47], v[132:135], v[202:205], v[44:47]
	v_mfma_f32_16x16x32_bf16 v[40:43], v[140:143], v[202:205], v[40:43]
	v_mfma_f32_16x16x32_bf16 v[28:31], v[132:135], v[210:213], v[28:31]
	v_mfma_f32_16x16x32_bf16 v[24:27], v[140:143], v[210:213], v[24:27]
	v_mfma_f32_16x16x32_bf16 v[12:15], v[132:135], v[218:221], v[12:15]
	v_mfma_f32_16x16x32_bf16 v[8:11], v[140:143], v[218:221], v[8:11]
	s_setprio 0
	s_setprio 1
	v_mfma_f32_16x16x32_bf16 v[52:55], v[162:165], v[190:193], v[52:55]
	v_mfma_f32_16x16x32_bf16 v[48:51], v[170:173], v[190:193], v[48:51]
	v_mfma_f32_16x16x32_bf16 v[36:39], v[162:165], v[198:201], v[36:39]
	v_mfma_f32_16x16x32_bf16 v[32:35], v[170:173], v[198:201], v[32:35]
	v_mfma_f32_16x16x32_bf16 v[20:23], v[162:165], v[206:209], v[20:23]
	v_mfma_f32_16x16x32_bf16 v[16:19], v[170:173], v[206:209], v[16:19]
	v_mfma_f32_16x16x32_bf16 v[4:7], v[162:165], v[214:217], v[4:7]
	v_mfma_f32_16x16x32_bf16 v[0:3], v[170:173], v[214:217], v[0:3]
	v_mfma_f32_16x16x32_bf16 v[52:55], v[166:169], v[194:197], v[52:55]
	v_mfma_f32_16x16x32_bf16 v[48:51], v[186:189], v[194:197], v[48:51]
	v_mfma_f32_16x16x32_bf16 v[36:39], v[166:169], v[202:205], v[36:39]
	v_mfma_f32_16x16x32_bf16 v[32:35], v[186:189], v[202:205], v[32:35]
	v_mfma_f32_16x16x32_bf16 v[20:23], v[166:169], v[210:213], v[20:23]
	v_mfma_f32_16x16x32_bf16 v[16:19], v[186:189], v[210:213], v[16:19]
	v_mfma_f32_16x16x32_bf16 v[4:7], v[166:169], v[218:221], v[4:7]
	v_mfma_f32_16x16x32_bf16 v[0:3], v[186:189], v[218:221], v[0:3]
	s_setprio 0
	s_barrier
	s_add_i32 s92, s92, 2
	s_add_u32 vcc_lo, vcc_lo, 0x100
	s_addc_u32 vcc_hi, vcc_hi, 0
	s_cmp_gt_u32 s92, 13
	s_mov_b64 s[6:7], s[8:9]
	s_cbranch_scc0 .LBB0_228
	s_and_b64 vcc, exec, s[82:83]
	s_cbranch_vccz .LBB0_231
	s_barrier

.LBB0_448:
	v_add_u32_e32 v1, s78, v210
	ds_read_b128 v[132:135], v1
	ds_read_b128 v[136:139], v1 offset:1024
	ds_read_b128 v[140:143], v1 offset:2048
	ds_read_b128 v[144:147], v1 offset:3072
	v_add_u32_e32 v1, s79, v210
	s_add_u32 s48, s38, s46
	ds_read_b128 v[148:151], v1
	ds_read_b128 v[152:155], v1 offset:1024
	ds_read_b128 v[156:159], v1 offset:2048
	ds_read_b128 v[160:163], v1 offset:3072
	s_addc_u32 s49, s39, s47
	s_add_u32 s48, s48, 0x10000
	s_addc_u32 s49, s49, 0
	s_cmp_eq_u32 s46, 0xf0000
	s_cselect_b32 s64, s81, s48
	s_cselect_b32 s65, s21, s49
	s_cselect_b32 s50, s83, s41
	s_cselect_b32 s51, s19, s86
	s_add_u32 s48, s64, 0x8000
	s_addc_u32 s49, s65, 0
	v_lshl_add_u64 v[2:3], v[204:205], 0, s[46:47]
	s_add_i32 m0, s35, 0xc000
	ds_read_b128 v[164:167], v211
	ds_read_b128 v[168:171], v211 offset:1024
	ds_read_b128 v[172:175], v211 offset:2048
	ds_read_b128 v[176:179], v211 offset:3072
	ds_read_b128 v[180:183], v211 offset:4096
	ds_read_b128 v[184:187], v211 offset:5120
	ds_read_b128 v[212:215], v211 offset:6144
	ds_read_b128 v[216:219], v211 offset:7168
	global_load_lds_dwordx4 v[2:3], off
	v_lshl_add_u64 v[2:3], v[206:207], 0, s[46:47]
	s_add_i32 m0, s35, 0xe000
	s_nop 0
	global_load_lds_dwordx4 v[2:3], off
	s_waitcnt vmcnt(8)
	s_waitcnt lgkmcnt(0)
	s_barrier
	s_setprio 1
	s_waitcnt lgkmcnt(0)
	v_mfma_f32_16x16x32_bf16 v[128:131], v[132:135], v[164:167], v[128:131]
	v_mfma_f32_16x16x32_bf16 v[124:127], v[140:143], v[164:167], v[124:127]
	v_mfma_f32_16x16x32_bf16 v[112:115], v[132:135], v[172:175], v[112:115]
	v_mfma_f32_16x16x32_bf16 v[108:111], v[140:143], v[172:175], v[108:111]
	v_mfma_f32_16x16x32_bf16 v[96:99], v[132:135], v[180:183], v[96:99]
	v_mfma_f32_16x16x32_bf16 v[92:95], v[140:143], v[180:183], v[92:95]
	v_mfma_f32_16x16x32_bf16 v[80:83], v[132:135], v[212:215], v[80:83]
	v_mfma_f32_16x16x32_bf16 v[76:79], v[140:143], v[212:215], v[76:79]
	v_mfma_f32_16x16x32_bf16 v[128:131], v[136:139], v[168:171], v[128:131]
	v_mfma_f32_16x16x32_bf16 v[124:127], v[144:147], v[168:171], v[124:127]
	v_mfma_f32_16x16x32_bf16 v[112:115], v[136:139], v[176:179], v[112:115]
	v_mfma_f32_16x16x32_bf16 v[108:111], v[144:147], v[176:179], v[108:111]
	v_mfma_f32_16x16x32_bf16 v[96:99], v[136:139], v[184:187], v[96:99]
	v_mfma_f32_16x16x32_bf16 v[92:95], v[144:147], v[184:187], v[92:95]
	v_mfma_f32_16x16x32_bf16 v[80:83], v[136:139], v[216:219], v[80:83]
	v_mfma_f32_16x16x32_bf16 v[76:79], v[144:147], v[216:219], v[76:79]
	s_setprio 0
	s_setprio 1
	v_mfma_f32_16x16x32_bf16 v[120:123], v[148:151], v[164:167], v[120:123]
	v_mfma_f32_16x16x32_bf16 v[116:119], v[156:159], v[164:167], v[116:119]
	v_mfma_f32_16x16x32_bf16 v[104:107], v[148:151], v[172:175], v[104:107]
	v_mfma_f32_16x16x32_bf16 v[100:103], v[156:159], v[172:175], v[100:103]
	v_mfma_f32_16x16x32_bf16 v[88:91], v[148:151], v[180:183], v[88:91]
	v_mfma_f32_16x16x32_bf16 v[84:87], v[156:159], v[180:183], v[84:87]
	v_mfma_f32_16x16x32_bf16 v[72:75], v[148:151], v[212:215], v[72:75]
	v_mfma_f32_16x16x32_bf16 v[68:71], v[156:159], v[212:215], v[68:71]
	v_mfma_f32_16x16x32_bf16 v[120:123], v[152:155], v[168:171], v[120:123]
	v_mfma_f32_16x16x32_bf16 v[116:119], v[160:163], v[168:171], v[116:119]
	v_mfma_f32_16x16x32_bf16 v[104:107], v[152:155], v[176:179], v[104:107]
	v_mfma_f32_16x16x32_bf16 v[100:103], v[160:163], v[176:179], v[100:103]
	v_mfma_f32_16x16x32_bf16 v[88:91], v[152:155], v[184:187], v[88:91]
	v_mfma_f32_16x16x32_bf16 v[84:87], v[160:163], v[184:187], v[84:87]
	v_mfma_f32_16x16x32_bf16 v[72:75], v[152:155], v[216:219], v[72:75]
	v_mfma_f32_16x16x32_bf16 v[68:71], v[160:163], v[216:219], v[68:71]
	s_setprio 0
	s_barrier
	s_add_i32 s88, s78, s34
	s_mov_b32 m0, s88
	ds_read_b128 v[164:167], v211 offset:16384
	ds_read_b128 v[168:171], v211 offset:17408
	ds_read_b128 v[172:175], v211 offset:18432
	ds_read_b128 v[176:179], v211 offset:19456
	ds_read_b128 v[180:183], v211 offset:20480
	ds_read_b128 v[184:187], v211 offset:21504
	ds_read_b128 v[212:215], v211 offset:22528
	ds_read_b128 v[216:219], v211 offset:23552
	global_load_lds_dwordx4 v192, s[50:51]
	s_add_i32 m0, s88, 0x2000
	s_add_u32 s88, s50, 0x80000
	v_lshl_add_u64 v[222:223], s[50:51], 0, v[188:189]
	s_addc_u32 s89, s51, 0
	s_add_i32 s90, s79, s34
	global_load_lds_dwordx4 v[222:223], off
	s_mov_b32 m0, s90
	s_nop 0
	global_load_lds_dwordx4 v192, s[88:89]
	s_add_i32 m0, s90, 0x2000
	s_nop 0
	global_load_lds_dwordx4 v188, s[88:89]
	s_mov_b32 m0, s35
	s_nop 0
	global_load_lds_dwordx4 v194, s[64:65]
	s_mov_b32 m0, s56
	s_nop 0
	global_load_lds_dwordx4 v190, s[64:65]
	s_waitcnt vmcnt(8)
	s_waitcnt lgkmcnt(0)
	s_barrier
	s_setprio 1
	s_waitcnt lgkmcnt(0)
	v_mfma_f32_16x16x32_bf16 v[64:67], v[132:135], v[164:167], v[64:67]
	v_mfma_f32_16x16x32_bf16 v[60:63], v[140:143], v[164:167], v[60:63]
	v_mfma_f32_16x16x32_bf16 v[48:51], v[132:135], v[172:175], v[48:51]
	v_mfma_f32_16x16x32_bf16 v[44:47], v[140:143], v[172:175], v[44:47]
	v_mfma_f32_16x16x32_bf16 v[32:35], v[132:135], v[180:183], v[32:35]
	v_mfma_f32_16x16x32_bf16 v[28:31], v[140:143], v[180:183], v[28:31]
	v_mfma_f32_16x16x32_bf16 v[16:19], v[132:135], v[212:215], v[16:19]
	v_mfma_f32_16x16x32_bf16 v[12:15], v[140:143], v[212:215], v[12:15]
	v_mfma_f32_16x16x32_bf16 v[64:67], v[136:139], v[168:171], v[64:67]
	v_mfma_f32_16x16x32_bf16 v[60:63], v[144:147], v[168:171], v[60:63]
	v_mfma_f32_16x16x32_bf16 v[48:51], v[136:139], v[176:179], v[48:51]
	v_mfma_f32_16x16x32_bf16 v[44:47], v[144:147], v[176:179], v[44:47]
	v_mfma_f32_16x16x32_bf16 v[32:35], v[136:139], v[184:187], v[32:35]
	v_mfma_f32_16x16x32_bf16 v[28:31], v[144:147], v[184:187], v[28:31]
	v_mfma_f32_16x16x32_bf16 v[16:19], v[136:139], v[216:219], v[16:19]
	v_mfma_f32_16x16x32_bf16 v[12:15], v[144:147], v[216:219], v[12:15]
	s_setprio 0
	s_setprio 1
	v_mfma_f32_16x16x32_bf16 v[56:59], v[148:151], v[164:167], v[56:59]
	v_mfma_f32_16x16x32_bf16 v[52:55], v[156:159], v[164:167], v[52:55]
	v_mfma_f32_16x16x32_bf16 v[40:43], v[148:151], v[172:175], v[40:43]
	v_mfma_f32_16x16x32_bf16 v[36:39], v[156:159], v[172:175], v[36:39]
	v_mfma_f32_16x16x32_bf16 v[24:27], v[148:151], v[180:183], v[24:27]
	v_mfma_f32_16x16x32_bf16 v[20:23], v[156:159], v[180:183], v[20:23]
	v_mfma_f32_16x16x32_bf16 v[8:11], v[148:151], v[212:215], v[8:11]
	v_mfma_f32_16x16x32_bf16 v[2:5], v[156:159], v[212:215], v[4:7]
	v_mfma_f32_16x16x32_bf16 v[56:59], v[152:155], v[168:171], v[56:59]
	v_mfma_f32_16x16x32_bf16 v[52:55], v[160:163], v[168:171], v[52:55]
	v_mfma_f32_16x16x32_bf16 v[40:43], v[152:155], v[176:179], v[40:43]
	v_mfma_f32_16x16x32_bf16 v[36:39], v[160:163], v[176:179], v[36:39]
	v_mfma_f32_16x16x32_bf16 v[24:27], v[152:155], v[184:187], v[24:27]
	v_mfma_f32_16x16x32_bf16 v[20:23], v[160:163], v[184:187], v[20:23]
	v_mfma_f32_16x16x32_bf16 v[8:11], v[152:155], v[216:219], v[8:11]
	v_mfma_f32_16x16x32_bf16 v[2:5], v[160:163], v[216:219], v[2:5]
	s_setprio 0
	s_barrier
	s_add_i32 s88, 0, 0x18000
	v_add_u32_e32 v1, s88, v210
	s_add_i32 s89, 0, 0x1c000
	ds_read_b128 v[132:135], v1
	ds_read_b128 v[136:139], v1 offset:1024
	ds_read_b128 v[140:143], v1 offset:2048
	ds_read_b128 v[144:147], v1 offset:3072
	v_add_u32_e32 v1, s89, v210
	ds_read_b128 v[148:151], v1
	ds_read_b128 v[152:155], v1 offset:1024
	ds_read_b128 v[156:159], v1 offset:2048
	ds_read_b128 v[160:163], v1 offset:3072
	s_add_u32 s64, s64, 0x2000
	s_addc_u32 s65, s65, 0
	s_mov_b32 m0, s57
	ds_read_b128 v[164:167], v211 offset:32768
	ds_read_b128 v[168:171], v211 offset:33792
	ds_read_b128 v[172:175], v211 offset:34816
	ds_read_b128 v[176:179], v211 offset:35840
	ds_read_b128 v[180:183], v211 offset:36864
	ds_read_b128 v[184:187], v211 offset:37888
	ds_read_b128 v[212:215], v211 offset:38912
	ds_read_b128 v[216:219], v211 offset:39936
	global_load_lds_dwordx4 v194, s[64:65]
	s_mov_b32 m0, s59
	s_nop 0
	global_load_lds_dwordx4 v190, s[64:65]
	s_waitcnt vmcnt(8)
	s_waitcnt lgkmcnt(0)
	s_barrier
	s_setprio 1
	s_waitcnt lgkmcnt(0)
	v_mfma_f32_16x16x32_bf16 v[128:131], v[132:135], v[164:167], v[128:131]
	v_mfma_f32_16x16x32_bf16 v[124:127], v[140:143], v[164:167], v[124:127]
	v_mfma_f32_16x16x32_bf16 v[112:115], v[132:135], v[172:175], v[112:115]
	v_mfma_f32_16x16x32_bf16 v[108:111], v[140:143], v[172:175], v[108:111]
	v_mfma_f32_16x16x32_bf16 v[96:99], v[132:135], v[180:183], v[96:99]
	v_mfma_f32_16x16x32_bf16 v[92:95], v[140:143], v[180:183], v[92:95]
	v_mfma_f32_16x16x32_bf16 v[80:83], v[132:135], v[212:215], v[80:83]
	v_mfma_f32_16x16x32_bf16 v[76:79], v[140:143], v[212:215], v[76:79]
	v_mfma_f32_16x16x32_bf16 v[128:131], v[136:139], v[168:171], v[128:131]
	v_mfma_f32_16x16x32_bf16 v[124:127], v[144:147], v[168:171], v[124:127]
	v_mfma_f32_16x16x32_bf16 v[112:115], v[136:139], v[176:179], v[112:115]
	v_mfma_f32_16x16x32_bf16 v[108:111], v[144:147], v[176:179], v[108:111]
	v_mfma_f32_16x16x32_bf16 v[96:99], v[136:139], v[184:187], v[96:99]
	v_mfma_f32_16x16x32_bf16 v[92:95], v[144:147], v[184:187], v[92:95]
	v_mfma_f32_16x16x32_bf16 v[80:83], v[136:139], v[216:219], v[80:83]
	v_mfma_f32_16x16x32_bf16 v[76:79], v[144:147], v[216:219], v[76:79]
	s_setprio 0
	s_setprio 1
	v_mfma_f32_16x16x32_bf16 v[120:123], v[148:151], v[164:167], v[120:123]
	v_mfma_f32_16x16x32_bf16 v[116:119], v[156:159], v[164:167], v[116:119]
	v_mfma_f32_16x16x32_bf16 v[104:107], v[148:151], v[172:175], v[104:107]
	v_mfma_f32_16x16x32_bf16 v[100:103], v[156:159], v[172:175], v[100:103]
	v_mfma_f32_16x16x32_bf16 v[88:91], v[148:151], v[180:183], v[88:91]
	v_mfma_f32_16x16x32_bf16 v[84:87], v[156:159], v[180:183], v[84:87]
	v_mfma_f32_16x16x32_bf16 v[72:75], v[148:151], v[212:215], v[72:75]
	v_mfma_f32_16x16x32_bf16 v[68:71], v[156:159], v[212:215], v[68:71]
	v_mfma_f32_16x16x32_bf16 v[120:123], v[152:155], v[168:171], v[120:123]
	v_mfma_f32_16x16x32_bf16 v[116:119], v[160:163], v[168:171], v[116:119]
	v_mfma_f32_16x16x32_bf16 v[104:107], v[152:155], v[176:179], v[104:107]
	v_mfma_f32_16x16x32_bf16 v[100:103], v[160:163], v[176:179], v[100:103]
	v_mfma_f32_16x16x32_bf16 v[88:91], v[152:155], v[184:187], v[88:91]
	v_mfma_f32_16x16x32_bf16 v[84:87], v[160:163], v[184:187], v[84:87]
	v_mfma_f32_16x16x32_bf16 v[72:75], v[152:155], v[216:219], v[72:75]
	v_mfma_f32_16x16x32_bf16 v[68:71], v[160:163], v[216:219], v[68:71]
	s_setprio 0
	s_barrier
	s_add_u32 s98, s50, s10
	s_addc_u32 s99, s51, s11
	s_add_i32 s64, s88, s34
	s_mov_b32 m0, s64
	ds_read_b128 v[164:167], v211 offset:49152
	ds_read_b128 v[168:171], v211 offset:50176
	ds_read_b128 v[172:175], v211 offset:51200
	ds_read_b128 v[176:179], v211 offset:52224
	ds_read_b128 v[180:183], v211 offset:53248
	ds_read_b128 v[184:187], v211 offset:54272
	ds_read_b128 v[212:215], v211 offset:55296
	ds_read_b128 v[216:219], v211 offset:56320
	global_load_lds_dwordx4 v192, s[98:99]
	s_add_i32 m0, s64, 0x2000
	s_add_u32 s50, s50, 0x80080
	v_lshl_add_u64 v[6:7], v[222:223], 0, s[10:11]
	s_addc_u32 s51, s51, 0
	s_add_i32 s64, s89, s34
	global_load_lds_dwordx4 v[6:7], off
	s_mov_b32 m0, s64
	s_nop 0
	global_load_lds_dwordx4 v192, s[50:51]
	s_add_i32 m0, s64, 0x2000
	s_nop 0
	global_load_lds_dwordx4 v188, s[50:51]
	s_mov_b32 m0, s74
	s_nop 0
	global_load_lds_dwordx4 v194, s[48:49]
	s_mov_b32 m0, s75
	s_nop 0
	global_load_lds_dwordx4 v190, s[48:49]
	s_waitcnt vmcnt(8)
	s_waitcnt lgkmcnt(0)
	s_barrier
	s_setprio 1
	s_waitcnt lgkmcnt(0)
	v_mfma_f32_16x16x32_bf16 v[64:67], v[132:135], v[164:167], v[64:67]
	v_mfma_f32_16x16x32_bf16 v[60:63], v[140:143], v[164:167], v[60:63]
	v_mfma_f32_16x16x32_bf16 v[48:51], v[132:135], v[172:175], v[48:51]
	v_mfma_f32_16x16x32_bf16 v[44:47], v[140:143], v[172:175], v[44:47]
	v_mfma_f32_16x16x32_bf16 v[32:35], v[132:135], v[180:183], v[32:35]
	v_mfma_f32_16x16x32_bf16 v[28:31], v[140:143], v[180:183], v[28:31]
	v_mfma_f32_16x16x32_bf16 v[16:19], v[132:135], v[212:215], v[16:19]
	v_mfma_f32_16x16x32_bf16 v[12:15], v[140:143], v[212:215], v[12:15]
	v_mfma_f32_16x16x32_bf16 v[64:67], v[136:139], v[168:171], v[64:67]
	v_mfma_f32_16x16x32_bf16 v[60:63], v[144:147], v[168:171], v[60:63]
	v_mfma_f32_16x16x32_bf16 v[48:51], v[136:139], v[176:179], v[48:51]
	v_mfma_f32_16x16x32_bf16 v[44:47], v[144:147], v[176:179], v[44:47]
	v_mfma_f32_16x16x32_bf16 v[32:35], v[136:139], v[184:187], v[32:35]
	v_mfma_f32_16x16x32_bf16 v[28:31], v[144:147], v[184:187], v[28:31]
	v_mfma_f32_16x16x32_bf16 v[16:19], v[136:139], v[216:219], v[16:19]
	v_mfma_f32_16x16x32_bf16 v[12:15], v[144:147], v[216:219], v[12:15]
	s_setprio 0
	s_setprio 1
	v_mfma_f32_16x16x32_bf16 v[56:59], v[148:151], v[164:167], v[56:59]
	v_mfma_f32_16x16x32_bf16 v[52:55], v[156:159], v[164:167], v[52:55]
	v_mfma_f32_16x16x32_bf16 v[40:43], v[148:151], v[172:175], v[40:43]
	v_mfma_f32_16x16x32_bf16 v[36:39], v[156:159], v[172:175], v[36:39]
	v_mfma_f32_16x16x32_bf16 v[24:27], v[148:151], v[180:183], v[24:27]
	v_mfma_f32_16x16x32_bf16 v[20:23], v[156:159], v[180:183], v[20:23]
	v_mfma_f32_16x16x32_bf16 v[6:9], v[148:151], v[212:215], v[8:11]
	v_mfma_f32_16x16x32_bf16 v[2:5], v[156:159], v[212:215], v[2:5]
	v_mfma_f32_16x16x32_bf16 v[56:59], v[152:155], v[168:171], v[56:59]
	v_mfma_f32_16x16x32_bf16 v[52:55], v[160:163], v[168:171], v[52:55]
	v_mfma_f32_16x16x32_bf16 v[40:43], v[152:155], v[176:179], v[40:43]
	v_mfma_f32_16x16x32_bf16 v[36:39], v[160:163], v[176:179], v[36:39]
	v_mfma_f32_16x16x32_bf16 v[24:27], v[152:155], v[184:187], v[24:27]
	v_mfma_f32_16x16x32_bf16 v[20:23], v[160:163], v[184:187], v[20:23]
	v_mfma_f32_16x16x32_bf16 v[8:11], v[152:155], v[216:219], v[6:9]
	v_mfma_f32_16x16x32_bf16 v[4:7], v[160:163], v[216:219], v[2:5]
	s_setprio 0
	s_barrier
	s_add_i32 s87, s87, 2
	s_add_u32 s41, s41, 0x100
	s_addc_u32 s86, s86, 0
	s_add_u32 s46, s46, 0x10000
	s_addc_u32 s47, s47, 0
	s_cmp_gt_u32 s87, 29
	s_cbranch_scc1 .LBB0_440

.LBB0_507:
	ds_read_b128 v[128:131], v229
	ds_read_b128 v[132:135], v229 offset:1024
	ds_read_b128 v[136:139], v229 offset:2048
	ds_read_b128 v[140:143], v229 offset:3072
	ds_read_b128 v[144:147], v230
	ds_read_b128 v[148:151], v230 offset:1024
	ds_read_b128 v[152:155], v230 offset:2048
	ds_read_b128 v[156:159], v230 offset:3072
	s_add_u32 s44, s42, 0x10000
	s_addc_u32 s45, s43, 0
	s_cmp_eq_u32 s83, 12
	s_cselect_b32 s50, s21, s44
	s_cselect_b32 s51, s8, s45
	s_cselect_b32 s48, s29, s80
	s_cselect_b32 s49, s27, s81
	s_add_u32 s46, s50, 0x8000
	s_addc_u32 s47, s51, 0
	s_add_i32 m0, s23, 0xc000
	ds_read_b128 v[160:163], v231
	ds_read_b128 v[164:167], v231 offset:1024
	ds_read_b128 v[168:171], v231 offset:2048
	ds_read_b128 v[172:175], v231 offset:3072
	ds_read_b128 v[176:179], v231 offset:4096
	ds_read_b128 v[180:183], v231 offset:5120
	ds_read_b128 v[184:187], v231 offset:6144
	ds_read_b128 v[188:191], v231 offset:7168
	global_load_lds_dwordx4 v200, s[42:43]
	s_add_i32 m0, s23, 0xe000
	s_nop 0
	global_load_lds_dwordx4 v202, s[42:43]
	s_waitcnt vmcnt(8)
	s_waitcnt lgkmcnt(0)
	s_barrier
	s_setprio 1
	s_waitcnt lgkmcnt(0)
	v_mfma_f32_16x16x32_bf16 v[124:127], v[128:131], v[160:163], v[124:127]
	v_mfma_f32_16x16x32_bf16 v[120:123], v[136:139], v[160:163], v[120:123]
	v_mfma_f32_16x16x32_bf16 v[108:111], v[128:131], v[168:171], v[108:111]
	v_mfma_f32_16x16x32_bf16 v[104:107], v[136:139], v[168:171], v[104:107]
	v_mfma_f32_16x16x32_bf16 v[92:95], v[128:131], v[176:179], v[92:95]
	v_mfma_f32_16x16x32_bf16 v[88:91], v[136:139], v[176:179], v[88:91]
	v_mfma_f32_16x16x32_bf16 v[76:79], v[128:131], v[184:187], v[76:79]
	v_mfma_f32_16x16x32_bf16 v[72:75], v[136:139], v[184:187], v[72:75]
	v_mfma_f32_16x16x32_bf16 v[124:127], v[132:135], v[164:167], v[124:127]
	v_mfma_f32_16x16x32_bf16 v[120:123], v[140:143], v[164:167], v[120:123]
	v_mfma_f32_16x16x32_bf16 v[108:111], v[132:135], v[172:175], v[108:111]
	v_mfma_f32_16x16x32_bf16 v[104:107], v[140:143], v[172:175], v[104:107]
	v_mfma_f32_16x16x32_bf16 v[92:95], v[132:135], v[180:183], v[92:95]
	v_mfma_f32_16x16x32_bf16 v[88:91], v[140:143], v[180:183], v[88:91]
	v_mfma_f32_16x16x32_bf16 v[76:79], v[132:135], v[188:191], v[76:79]
	v_mfma_f32_16x16x32_bf16 v[72:75], v[140:143], v[188:191], v[72:75]
	s_setprio 0
	s_setprio 1
	v_mfma_f32_16x16x32_bf16 v[116:119], v[144:147], v[160:163], v[116:119]
	v_mfma_f32_16x16x32_bf16 v[112:115], v[152:155], v[160:163], v[112:115]
	v_mfma_f32_16x16x32_bf16 v[100:103], v[144:147], v[168:171], v[100:103]
	v_mfma_f32_16x16x32_bf16 v[96:99], v[152:155], v[168:171], v[96:99]
	v_mfma_f32_16x16x32_bf16 v[84:87], v[144:147], v[176:179], v[84:87]
	v_mfma_f32_16x16x32_bf16 v[80:83], v[152:155], v[176:179], v[80:83]
	v_mfma_f32_16x16x32_bf16 v[68:71], v[144:147], v[184:187], v[68:71]
	v_mfma_f32_16x16x32_bf16 v[64:67], v[152:155], v[184:187], v[64:67]
	v_mfma_f32_16x16x32_bf16 v[116:119], v[148:151], v[164:167], v[116:119]
	v_mfma_f32_16x16x32_bf16 v[112:115], v[156:159], v[164:167], v[112:115]
	v_mfma_f32_16x16x32_bf16 v[100:103], v[148:151], v[172:175], v[100:103]
	v_mfma_f32_16x16x32_bf16 v[96:99], v[156:159], v[172:175], v[96:99]
	v_mfma_f32_16x16x32_bf16 v[84:87], v[148:151], v[180:183], v[84:87]
	v_mfma_f32_16x16x32_bf16 v[80:83], v[156:159], v[180:183], v[80:83]
	v_mfma_f32_16x16x32_bf16 v[68:71], v[148:151], v[188:191], v[68:71]
	v_mfma_f32_16x16x32_bf16 v[64:67], v[156:159], v[188:191], v[64:67]
	s_setprio 0
	s_barrier
	s_add_i32 s42, s77, s35
	s_mov_b32 m0, s42
	ds_read_b128 v[160:163], v231 offset:16384
	ds_read_b128 v[164:167], v231 offset:17408
	ds_read_b128 v[168:171], v231 offset:18432
	ds_read_b128 v[172:175], v231 offset:19456
	ds_read_b128 v[176:179], v231 offset:20480
	ds_read_b128 v[180:183], v231 offset:21504
	ds_read_b128 v[184:187], v231 offset:22528
	ds_read_b128 v[188:191], v231 offset:23552
	global_load_lds_dwordx4 v194, s[48:49]
	s_add_i32 m0, s42, 0x2000
	s_add_u32 s42, s48, 0x40000
	s_addc_u32 s43, s49, 0
	s_add_i32 s84, s78, s35
	global_load_lds_dwordx4 v198, s[48:49]
	s_mov_b32 m0, s84
	s_nop 0
	global_load_lds_dwordx4 v194, s[42:43]
	s_add_i32 m0, s84, 0x2000
	s_nop 0
	global_load_lds_dwordx4 v198, s[42:43]
	s_mov_b32 m0, s23
	s_nop 0
	global_load_lds_dwordx4 v192, s[50:51]
	s_mov_b32 m0, s56
	s_nop 0
	global_load_lds_dwordx4 v196, s[50:51]
	s_waitcnt vmcnt(8)
	s_waitcnt lgkmcnt(0)
	s_barrier
	s_setprio 1
	s_waitcnt lgkmcnt(0)
	v_mfma_f32_16x16x32_bf16 v[60:63], v[128:131], v[160:163], v[60:63]
	v_mfma_f32_16x16x32_bf16 v[56:59], v[136:139], v[160:163], v[56:59]
	v_mfma_f32_16x16x32_bf16 v[44:47], v[128:131], v[168:171], v[44:47]
	v_mfma_f32_16x16x32_bf16 v[40:43], v[136:139], v[168:171], v[40:43]
	v_mfma_f32_16x16x32_bf16 v[28:31], v[128:131], v[176:179], v[28:31]
	v_mfma_f32_16x16x32_bf16 v[24:27], v[136:139], v[176:179], v[24:27]
	v_mfma_f32_16x16x32_bf16 v[12:15], v[128:131], v[184:187], v[12:15]
	v_mfma_f32_16x16x32_bf16 v[8:11], v[136:139], v[184:187], v[8:11]
	v_mfma_f32_16x16x32_bf16 v[60:63], v[132:135], v[164:167], v[60:63]
	v_mfma_f32_16x16x32_bf16 v[56:59], v[140:143], v[164:167], v[56:59]
	v_mfma_f32_16x16x32_bf16 v[44:47], v[132:135], v[172:175], v[44:47]
	v_mfma_f32_16x16x32_bf16 v[40:43], v[140:143], v[172:175], v[40:43]
	v_mfma_f32_16x16x32_bf16 v[28:31], v[132:135], v[180:183], v[28:31]
	v_mfma_f32_16x16x32_bf16 v[24:27], v[140:143], v[180:183], v[24:27]
	v_mfma_f32_16x16x32_bf16 v[12:15], v[132:135], v[188:191], v[12:15]
	v_mfma_f32_16x16x32_bf16 v[8:11], v[140:143], v[188:191], v[8:11]
	s_setprio 0
	s_setprio 1
	v_mfma_f32_16x16x32_bf16 v[52:55], v[144:147], v[160:163], v[52:55]
	v_mfma_f32_16x16x32_bf16 v[48:51], v[152:155], v[160:163], v[48:51]
	v_mfma_f32_16x16x32_bf16 v[36:39], v[144:147], v[168:171], v[36:39]
	v_mfma_f32_16x16x32_bf16 v[32:35], v[152:155], v[168:171], v[32:35]
	v_mfma_f32_16x16x32_bf16 v[20:23], v[144:147], v[176:179], v[20:23]
	v_mfma_f32_16x16x32_bf16 v[16:19], v[152:155], v[176:179], v[16:19]
	v_mfma_f32_16x16x32_bf16 v[4:7], v[144:147], v[184:187], v[4:7]
	v_mfma_f32_16x16x32_bf16 v[0:3], v[152:155], v[184:187], v[0:3]
	v_mfma_f32_16x16x32_bf16 v[52:55], v[148:151], v[164:167], v[52:55]
	v_mfma_f32_16x16x32_bf16 v[48:51], v[156:159], v[164:167], v[48:51]
	v_mfma_f32_16x16x32_bf16 v[36:39], v[148:151], v[172:175], v[36:39]
	v_mfma_f32_16x16x32_bf16 v[32:35], v[156:159], v[172:175], v[32:35]
	v_mfma_f32_16x16x32_bf16 v[20:23], v[148:151], v[180:183], v[20:23]
	v_mfma_f32_16x16x32_bf16 v[16:19], v[156:159], v[180:183], v[16:19]
	v_mfma_f32_16x16x32_bf16 v[4:7], v[148:151], v[188:191], v[4:7]
	v_mfma_f32_16x16x32_bf16 v[0:3], v[156:159], v[188:191], v[0:3]
	s_setprio 0
	s_barrier
	s_add_i32 s84, 0, 0x18000
	s_add_i32 s85, 0, 0x1c000
	v_add_u32_e32 v140, s84, v228
	v_add_u32_e32 v156, s85, v228
	ds_read_b128 v[128:131], v140
	ds_read_b128 v[132:135], v140 offset:1024
	ds_read_b128 v[136:139], v140 offset:2048
	ds_read_b128 v[140:143], v140 offset:3072
	ds_read_b128 v[144:147], v156
	ds_read_b128 v[148:151], v156 offset:1024
	ds_read_b128 v[152:155], v156 offset:2048
	ds_read_b128 v[156:159], v156 offset:3072
	s_add_u32 s42, s50, 0x2000
	s_addc_u32 s43, s51, 0
	s_mov_b32 m0, s57
	ds_read_b128 v[160:163], v231 offset:32768
	ds_read_b128 v[164:167], v231 offset:33792
	ds_read_b128 v[168:171], v231 offset:34816
	ds_read_b128 v[172:175], v231 offset:35840
	ds_read_b128 v[176:179], v231 offset:36864
	ds_read_b128 v[180:183], v231 offset:37888
	ds_read_b128 v[184:187], v231 offset:38912
	ds_read_b128 v[188:191], v231 offset:39936
	global_load_lds_dwordx4 v192, s[42:43]
	s_mov_b32 m0, s59
	s_nop 0
	global_load_lds_dwordx4 v196, s[42:43]
	s_waitcnt vmcnt(8)
	s_waitcnt lgkmcnt(0)
	s_barrier
	s_setprio 1
	s_waitcnt lgkmcnt(0)
	v_mfma_f32_16x16x32_bf16 v[124:127], v[128:131], v[160:163], v[124:127]
	v_mfma_f32_16x16x32_bf16 v[120:123], v[136:139], v[160:163], v[120:123]
	v_mfma_f32_16x16x32_bf16 v[108:111], v[128:131], v[168:171], v[108:111]
	v_mfma_f32_16x16x32_bf16 v[104:107], v[136:139], v[168:171], v[104:107]
	v_mfma_f32_16x16x32_bf16 v[92:95], v[128:131], v[176:179], v[92:95]
	v_mfma_f32_16x16x32_bf16 v[88:91], v[136:139], v[176:179], v[88:91]
	v_mfma_f32_16x16x32_bf16 v[76:79], v[128:131], v[184:187], v[76:79]
	v_mfma_f32_16x16x32_bf16 v[72:75], v[136:139], v[184:187], v[72:75]
	v_mfma_f32_16x16x32_bf16 v[124:127], v[132:135], v[164:167], v[124:127]
	v_mfma_f32_16x16x32_bf16 v[120:123], v[140:143], v[164:167], v[120:123]
	v_mfma_f32_16x16x32_bf16 v[108:111], v[132:135], v[172:175], v[108:111]
	v_mfma_f32_16x16x32_bf16 v[104:107], v[140:143], v[172:175], v[104:107]
	v_mfma_f32_16x16x32_bf16 v[92:95], v[132:135], v[180:183], v[92:95]
	v_mfma_f32_16x16x32_bf16 v[88:91], v[140:143], v[180:183], v[88:91]
	v_mfma_f32_16x16x32_bf16 v[76:79], v[132:135], v[188:191], v[76:79]
	v_mfma_f32_16x16x32_bf16 v[72:75], v[140:143], v[188:191], v[72:75]
	s_setprio 0
	s_setprio 1
	v_mfma_f32_16x16x32_bf16 v[116:119], v[144:147], v[160:163], v[116:119]
	v_mfma_f32_16x16x32_bf16 v[112:115], v[152:155], v[160:163], v[112:115]
	v_mfma_f32_16x16x32_bf16 v[100:103], v[144:147], v[168:171], v[100:103]
	v_mfma_f32_16x16x32_bf16 v[96:99], v[152:155], v[168:171], v[96:99]
	v_mfma_f32_16x16x32_bf16 v[84:87], v[144:147], v[176:179], v[84:87]
	v_mfma_f32_16x16x32_bf16 v[80:83], v[152:155], v[176:179], v[80:83]
	v_mfma_f32_16x16x32_bf16 v[68:71], v[144:147], v[184:187], v[68:71]
	v_mfma_f32_16x16x32_bf16 v[64:67], v[152:155], v[184:187], v[64:67]
	v_mfma_f32_16x16x32_bf16 v[116:119], v[148:151], v[164:167], v[116:119]
	v_mfma_f32_16x16x32_bf16 v[112:115], v[156:159], v[164:167], v[112:115]
	v_mfma_f32_16x16x32_bf16 v[100:103], v[148:151], v[172:175], v[100:103]
	v_mfma_f32_16x16x32_bf16 v[96:99], v[156:159], v[172:175], v[96:99]
	v_mfma_f32_16x16x32_bf16 v[84:87], v[148:151], v[180:183], v[84:87]
	v_mfma_f32_16x16x32_bf16 v[80:83], v[156:159], v[180:183], v[80:83]
	v_mfma_f32_16x16x32_bf16 v[68:71], v[148:151], v[188:191], v[68:71]
	v_mfma_f32_16x16x32_bf16 v[64:67], v[156:159], v[188:191], v[64:67]
	s_setprio 0
	s_barrier
	s_add_u32 s98, s48, s16
	s_addc_u32 s99, s49, s17
	s_add_i32 s42, s84, s35
	s_mov_b32 m0, s42
	ds_read_b128 v[160:163], v231 offset:49152
	ds_read_b128 v[164:167], v231 offset:50176
	ds_read_b128 v[168:171], v231 offset:51200
	ds_read_b128 v[172:175], v231 offset:52224
	ds_read_b128 v[176:179], v231 offset:53248
	ds_read_b128 v[180:183], v231 offset:54272
	ds_read_b128 v[184:187], v231 offset:55296
	ds_read_b128 v[188:191], v231 offset:56320
	global_load_lds_dwordx4 v194, s[98:99]
	s_add_i32 m0, s42, 0x2000
	s_add_u32 s42, s48, 0x40080
	s_addc_u32 s43, s49, 0
	s_add_i32 s48, s85, s35
	global_load_lds_dwordx4 v198, s[98:99]
	s_mov_b32 m0, s48
	s_nop 0
	global_load_lds_dwordx4 v194, s[42:43]
	s_add_i32 m0, s48, 0x2000
	s_nop 0
	global_load_lds_dwordx4 v198, s[42:43]
	s_mov_b32 m0, s75
	s_nop 0
	global_load_lds_dwordx4 v192, s[46:47]
	s_mov_b32 m0, s76
	s_nop 0
	global_load_lds_dwordx4 v196, s[46:47]
	s_waitcnt vmcnt(8)
	s_waitcnt lgkmcnt(0)
	s_barrier
	s_setprio 1
	s_waitcnt lgkmcnt(0)
	v_mfma_f32_16x16x32_bf16 v[60:63], v[128:131], v[160:163], v[60:63]
	v_mfma_f32_16x16x32_bf16 v[56:59], v[136:139], v[160:163], v[56:59]
	v_mfma_f32_16x16x32_bf16 v[44:47], v[128:131], v[168:171], v[44:47]
	v_mfma_f32_16x16x32_bf16 v[40:43], v[136:139], v[168:171], v[40:43]
	v_mfma_f32_16x16x32_bf16 v[28:31], v[128:131], v[176:179], v[28:31]
	v_mfma_f32_16x16x32_bf16 v[24:27], v[136:139], v[176:179], v[24:27]
	v_mfma_f32_16x16x32_bf16 v[12:15], v[128:131], v[184:187], v[12:15]
	v_mfma_f32_16x16x32_bf16 v[8:11], v[136:139], v[184:187], v[8:11]
	v_mfma_f32_16x16x32_bf16 v[60:63], v[132:135], v[164:167], v[60:63]
	v_mfma_f32_16x16x32_bf16 v[56:59], v[140:143], v[164:167], v[56:59]
	v_mfma_f32_16x16x32_bf16 v[44:47], v[132:135], v[172:175], v[44:47]
	v_mfma_f32_16x16x32_bf16 v[40:43], v[140:143], v[172:175], v[40:43]
	v_mfma_f32_16x16x32_bf16 v[28:31], v[132:135], v[180:183], v[28:31]
	v_mfma_f32_16x16x32_bf16 v[24:27], v[140:143], v[180:183], v[24:27]
	v_mfma_f32_16x16x32_bf16 v[12:15], v[132:135], v[188:191], v[12:15]
	v_mfma_f32_16x16x32_bf16 v[8:11], v[140:143], v[188:191], v[8:11]
	s_setprio 0
	s_setprio 1
	v_mfma_f32_16x16x32_bf16 v[52:55], v[144:147], v[160:163], v[52:55]
	v_mfma_f32_16x16x32_bf16 v[48:51], v[152:155], v[160:163], v[48:51]
	v_mfma_f32_16x16x32_bf16 v[36:39], v[144:147], v[168:171], v[36:39]
	v_mfma_f32_16x16x32_bf16 v[32:35], v[152:155], v[168:171], v[32:35]
	v_mfma_f32_16x16x32_bf16 v[20:23], v[144:147], v[176:179], v[20:23]
	v_mfma_f32_16x16x32_bf16 v[16:19], v[152:155], v[176:179], v[16:19]
	v_mfma_f32_16x16x32_bf16 v[4:7], v[144:147], v[184:187], v[4:7]
	v_mfma_f32_16x16x32_bf16 v[0:3], v[152:155], v[184:187], v[0:3]
	v_mfma_f32_16x16x32_bf16 v[52:55], v[148:151], v[164:167], v[52:55]
	v_mfma_f32_16x16x32_bf16 v[48:51], v[156:159], v[164:167], v[48:51]
	v_mfma_f32_16x16x32_bf16 v[36:39], v[148:151], v[172:175], v[36:39]
	v_mfma_f32_16x16x32_bf16 v[32:35], v[156:159], v[172:175], v[32:35]
	v_mfma_f32_16x16x32_bf16 v[20:23], v[148:151], v[180:183], v[20:23]
	v_mfma_f32_16x16x32_bf16 v[16:19], v[156:159], v[180:183], v[16:19]
	v_mfma_f32_16x16x32_bf16 v[4:7], v[148:151], v[188:191], v[4:7]
	v_mfma_f32_16x16x32_bf16 v[0:3], v[156:159], v[188:191], v[0:3]
	s_setprio 0
	s_barrier
	s_add_i32 s83, s83, 2
	s_add_u32 s80, s80, 0x100
	s_addc_u32 s81, s81, 0
	s_cmp_gt_u32 s83, 13
	s_mov_b64 s[42:43], s[44:45]
	s_cbranch_scc0 .LBB0_507
	v_mov_b32_e32 v233, v227
	v_mov_b32_e32 v144, v226
	s_lshl_b32 s8, s22, 8
	s_or_b32 s8, s8, s73
	v_lshlrev_b32_e32 v208, 3, v233
	v_add_u32_e32 v128, s8, v208
	s_lshr_b32 s8, s20, 4
	s_mul_i32 s42, s8, 0x1800
	s_ashr_i32 s43, s42, 31
	s_lshl_b64 s[42:43], s[42:43], 2
	s_add_u32 s42, s69, s42
	v_ashrrev_i32_e32 v129, 31, v128
	v_add_u32_e32 v210, s72, v144
	s_addc_u32 s43, s70, s43
	v_lshlrev_b64 v[212:213], 2, v[128:129]
	v_lshl_add_u32 v216, s20, 8, v210
	v_lshl_add_u64 v[214:215], s[42:43], 0, v[212:213]
	v_ashrrev_i32_e32 v217, 31, v216
	v_add_co_u32_e32 v128, vcc, s65, v214
	v_lshl_add_u64 v[218:219], s[36:37], 0, v[212:213]
	v_lshlrev_b64 v[144:145], 12, v[216:217]
	v_add_u32_e32 v224, 16, v216
	v_lshl_add_u64 v[132:133], v[214:215], 0, s[10:11]
	v_addc_co_u32_e32 v129, vcc, 0, v215, vcc
	v_lshl_add_u64 v[144:145], v[218:219], 0, v[144:145]
	v_ashrrev_i32_e32 v225, 31, v224
	global_load_dwordx4 v[140:143], v[128:129], off nt
	s_nop 0
	global_load_dwordx4 v[128:131], v[132:133], off offset:528 nt
	global_load_dwordx4 v[136:139], v[132:133], off offset:16 nt
	s_nop 0
	global_load_dwordx4 v[132:135], v[132:133], off offset:512 nt
	s_nop 0
	global_load_dwordx4 v[234:237], v[144:145], off offset:16 nt
	global_load_dwordx4 v[238:241], v[144:145], off nt
	global_load_dwordx4 v[242:245], v[144:145], off offset:528 nt
	global_load_dwordx4 v[246:249], v[144:145], off offset:512 nt
	v_lshlrev_b64 v[144:145], 12, v[224:225]
	v_add_u32_e32 v222, 32, v216
	v_lshl_add_u64 v[144:145], v[218:219], 0, v[144:145]
	v_ashrrev_i32_e32 v223, 31, v222
	global_load_dwordx4 v[184:187], v[144:145], off offset:16 nt
	global_load_dwordx4 v[188:191], v[144:145], off nt
	global_load_dwordx4 v[176:179], v[144:145], off offset:528 nt
	global_load_dwordx4 v[180:183], v[144:145], off offset:512 nt
	v_lshlrev_b64 v[144:145], 12, v[222:223]
	v_add_u32_e32 v220, 48, v216
	v_lshl_add_u64 v[144:145], v[218:219], 0, v[144:145]
	v_ashrrev_i32_e32 v221, 31, v220
	global_load_dwordx4 v[168:171], v[144:145], off offset:16 nt
	global_load_dwordx4 v[172:175], v[144:145], off nt
	global_load_dwordx4 v[160:163], v[144:145], off offset:528 nt
	global_load_dwordx4 v[164:167], v[144:145], off offset:512 nt
	v_lshlrev_b64 v[144:145], 12, v[220:221]
	v_lshl_add_u64 v[148:149], v[218:219], 0, v[144:145]
	global_load_dwordx4 v[152:155], v[148:149], off offset:16 nt
	global_load_dwordx4 v[156:159], v[148:149], off nt
	global_load_dwordx4 v[144:147], v[148:149], off offset:528 nt
	s_nop 0
	global_load_dwordx4 v[148:151], v[148:149], off offset:512 nt
	v_and_b32_e32 v211, 64, v232
	v_xor_b32_e32 v209, 16, v232
	v_add_u32_e32 v211, 64, v211
	v_cmp_lt_i32_e32 vcc, v209, v211
	v_xor_b32_e32 v250, 32, v232
	s_lshl_b32 s42, s22, 2
	v_cndmask_b32_e32 v209, v232, v209, vcc
	v_cmp_lt_i32_e32 vcc, v250, v211
	v_lshlrev_b32_e32 v209, 2, v209
	s_ashr_i32 s43, s42, 31
	v_cndmask_b32_e32 v211, v232, v250, vcc
	v_lshlrev_b32_e32 v211, 2, v211
	v_cmp_eq_u32_e32 vcc, 0, v233
	s_waitcnt vmcnt(0)
	v_pk_fma_f32 v[126:127], v[126:127], v[142:143], v[240:241]
	v_pk_fma_f32 v[124:125], v[124:125], v[140:141], v[238:239]
	v_pk_fma_f32 v[120:121], v[120:121], v[136:137], v[234:235]
	v_mul_f32_e32 v233, v125, v125
	v_mul_f32_e32 v234, v127, v127
	v_fmac_f32_e32 v233, v124, v124
	v_fmac_f32_e32 v234, v126, v126
	v_add_f32_e32 v233, v233, v234
	v_mul_f32_e32 v234, v121, v121
	v_pk_fma_f32 v[122:123], v[122:123], v[138:139], v[236:237]
	v_fmac_f32_e32 v234, v120, v120
	v_add_f32_e32 v233, v233, v234
	v_mul_f32_e32 v234, v123, v123
	v_fmac_f32_e32 v234, v122, v122
	v_pk_fma_f32 v[118:119], v[118:119], v[134:135], v[248:249]
	v_pk_fma_f32 v[116:117], v[116:117], v[132:133], v[246:247]
	v_add_f32_e32 v233, v234, v233
	v_mul_f32_e32 v234, v117, v117
	v_mul_f32_e32 v235, v119, v119
	v_pk_fma_f32 v[112:113], v[112:113], v[128:129], v[242:243]
	v_fmac_f32_e32 v234, v116, v116
	v_fmac_f32_e32 v235, v118, v118
	v_add_f32_e32 v234, v234, v235
	v_mul_f32_e32 v235, v113, v113
	v_pk_fma_f32 v[114:115], v[114:115], v[130:131], v[244:245]
	v_fmac_f32_e32 v235, v112, v112
	v_add_f32_e32 v234, v234, v235
	v_mul_f32_e32 v235, v115, v115
	v_fmac_f32_e32 v235, v114, v114
	v_add_f32_e32 v234, v235, v234
	v_add_f32_e32 v233, v233, v234
	ds_bpermute_b32 v234, v209, v233
	s_waitcnt lgkmcnt(0)
	v_add_f32_e32 v233, v233, v234
	ds_bpermute_b32 v234, v211, v233
	s_and_saveexec_b64 s[44:45], vcc
	s_cbranch_execz .LBB0_510
	v_lshlrev_b64 v[236:237], 6, v[216:217]
	v_lshl_add_u64 v[236:237], s[12:13], 0, v[236:237]
	v_lshl_add_u64 v[236:237], s[42:43], 2, v[236:237]
	s_lshl_b32 s8, s71, 2
	v_lshl_add_u64 v[236:237], v[236:237], 0, s[8:9]
	s_waitcnt lgkmcnt(0)
	v_add_f32_e32 v217, v233, v234
	global_store_dword v[236:237], v217, off

.LBB0_568:
	ds_read_b128 v[128:131], v167
	ds_read_b128 v[132:135], v167 offset:1024
	ds_read_b128 v[136:139], v167 offset:2048
	ds_read_b128 v[140:143], v167 offset:3072
	ds_read_b128 v[160:163], v168
	ds_read_b128 v[170:173], v168 offset:1024
	ds_read_b128 v[174:177], v168 offset:2048
	ds_read_b128 v[178:181], v168 offset:3072
	s_add_u32 s36, s28, 0x10000
	s_addc_u32 s37, s29, 0
	s_cmp_eq_u32 s76, 12
	s_cselect_b32 s42, s27, s36
	s_cselect_b32 s43, s19, s37
	s_cselect_b32 s40, s73, s74
	s_cselect_b32 s41, s17, s75
	s_add_u32 s38, s42, 0x8000
	s_addc_u32 s39, s43, 0
	s_add_i32 m0, s44, 0xc000
	ds_read_b128 v[182:185], v169
	ds_read_b128 v[186:189], v169 offset:1024
	ds_read_b128 v[190:193], v169 offset:2048
	ds_read_b128 v[194:197], v169 offset:3072
	ds_read_b128 v[198:201], v169 offset:4096
	ds_read_b128 v[202:205], v169 offset:5120
	ds_read_b128 v[206:209], v169 offset:6144
	ds_read_b128 v[210:213], v169 offset:7168
	global_load_lds_dwordx4 v152, s[28:29]
	s_add_i32 m0, s44, 0xe000
	s_nop 0
	global_load_lds_dwordx4 v154, s[28:29]
	s_waitcnt vmcnt(8)
	s_waitcnt lgkmcnt(0)
	s_barrier
	s_setprio 1
	s_waitcnt lgkmcnt(0)
	v_mfma_f32_16x16x32_bf16 v[124:127], v[128:131], v[182:185], v[124:127]
	v_mfma_f32_16x16x32_bf16 v[120:123], v[136:139], v[182:185], v[120:123]
	v_mfma_f32_16x16x32_bf16 v[116:119], v[128:131], v[190:193], v[116:119]
	v_mfma_f32_16x16x32_bf16 v[112:115], v[136:139], v[190:193], v[112:115]
	v_mfma_f32_16x16x32_bf16 v[92:95], v[128:131], v[198:201], v[92:95]
	v_mfma_f32_16x16x32_bf16 v[88:91], v[136:139], v[198:201], v[88:91]
	v_mfma_f32_16x16x32_bf16 v[76:79], v[128:131], v[206:209], v[76:79]
	v_mfma_f32_16x16x32_bf16 v[72:75], v[136:139], v[206:209], v[72:75]
	v_mfma_f32_16x16x32_bf16 v[124:127], v[132:135], v[186:189], v[124:127]
	v_mfma_f32_16x16x32_bf16 v[120:123], v[140:143], v[186:189], v[120:123]
	v_mfma_f32_16x16x32_bf16 v[116:119], v[132:135], v[194:197], v[116:119]
	v_mfma_f32_16x16x32_bf16 v[112:115], v[140:143], v[194:197], v[112:115]
	v_mfma_f32_16x16x32_bf16 v[92:95], v[132:135], v[202:205], v[92:95]
	v_mfma_f32_16x16x32_bf16 v[88:91], v[140:143], v[202:205], v[88:91]
	v_mfma_f32_16x16x32_bf16 v[76:79], v[132:135], v[210:213], v[76:79]
	v_mfma_f32_16x16x32_bf16 v[72:75], v[140:143], v[210:213], v[72:75]
	s_setprio 0
	s_setprio 1
	v_mfma_f32_16x16x32_bf16 v[108:111], v[160:163], v[182:185], v[108:111]
	v_mfma_f32_16x16x32_bf16 v[104:107], v[174:177], v[182:185], v[104:107]
	v_mfma_f32_16x16x32_bf16 v[100:103], v[160:163], v[190:193], v[100:103]
	v_mfma_f32_16x16x32_bf16 v[96:99], v[174:177], v[190:193], v[96:99]
	v_mfma_f32_16x16x32_bf16 v[84:87], v[160:163], v[198:201], v[84:87]
	v_mfma_f32_16x16x32_bf16 v[80:83], v[174:177], v[198:201], v[80:83]
	v_mfma_f32_16x16x32_bf16 v[68:71], v[160:163], v[206:209], v[68:71]
	v_mfma_f32_16x16x32_bf16 v[64:67], v[174:177], v[206:209], v[64:67]
	v_mfma_f32_16x16x32_bf16 v[108:111], v[170:173], v[186:189], v[108:111]
	v_mfma_f32_16x16x32_bf16 v[104:107], v[178:181], v[186:189], v[104:107]
	v_mfma_f32_16x16x32_bf16 v[100:103], v[170:173], v[194:197], v[100:103]
	v_mfma_f32_16x16x32_bf16 v[96:99], v[178:181], v[194:197], v[96:99]
	v_mfma_f32_16x16x32_bf16 v[84:87], v[170:173], v[202:205], v[84:87]
	v_mfma_f32_16x16x32_bf16 v[80:83], v[178:181], v[202:205], v[80:83]
	v_mfma_f32_16x16x32_bf16 v[68:71], v[170:173], v[210:213], v[68:71]
	v_mfma_f32_16x16x32_bf16 v[64:67], v[178:181], v[210:213], v[64:67]
	s_setprio 0
	s_barrier
	s_add_i32 s28, s70, s35
	s_mov_b32 m0, s28
	ds_read_b128 v[182:185], v169 offset:16384
	ds_read_b128 v[186:189], v169 offset:17408
	ds_read_b128 v[190:193], v169 offset:18432
	ds_read_b128 v[194:197], v169 offset:19456
	ds_read_b128 v[198:201], v169 offset:20480
	ds_read_b128 v[202:205], v169 offset:21504
	ds_read_b128 v[206:209], v169 offset:22528
	ds_read_b128 v[210:213], v169 offset:23552
	global_load_lds_dwordx4 v148, s[40:41]
	s_add_i32 m0, s28, 0x2000
	s_add_u32 s28, s40, 0x40000
	s_addc_u32 s29, s41, 0
	s_add_i32 s77, s71, s35
	global_load_lds_dwordx4 v144, s[40:41]
	s_mov_b32 m0, s77
	s_nop 0
	global_load_lds_dwordx4 v148, s[28:29]
	s_add_i32 m0, s77, 0x2000
	s_nop 0
	global_load_lds_dwordx4 v144, s[28:29]
	s_mov_b32 m0, s44
	s_nop 0
	global_load_lds_dwordx4 v150, s[42:43]
	s_mov_b32 m0, s45
	s_nop 0
	global_load_lds_dwordx4 v146, s[42:43]
	s_waitcnt vmcnt(8)
	s_waitcnt lgkmcnt(0)
	s_barrier
	s_setprio 1
	s_waitcnt lgkmcnt(0)
	v_mfma_f32_16x16x32_bf16 v[60:63], v[128:131], v[182:185], v[60:63]
	v_mfma_f32_16x16x32_bf16 v[56:59], v[136:139], v[182:185], v[56:59]
	v_mfma_f32_16x16x32_bf16 v[44:47], v[128:131], v[190:193], v[44:47]
	v_mfma_f32_16x16x32_bf16 v[40:43], v[136:139], v[190:193], v[40:43]
	v_mfma_f32_16x16x32_bf16 v[28:31], v[128:131], v[198:201], v[28:31]
	v_mfma_f32_16x16x32_bf16 v[24:27], v[136:139], v[198:201], v[24:27]
	v_mfma_f32_16x16x32_bf16 v[12:15], v[128:131], v[206:209], v[12:15]
	v_mfma_f32_16x16x32_bf16 v[8:11], v[136:139], v[206:209], v[8:11]
	v_mfma_f32_16x16x32_bf16 v[60:63], v[132:135], v[186:189], v[60:63]
	v_mfma_f32_16x16x32_bf16 v[56:59], v[140:143], v[186:189], v[56:59]
	v_mfma_f32_16x16x32_bf16 v[44:47], v[132:135], v[194:197], v[44:47]
	v_mfma_f32_16x16x32_bf16 v[40:43], v[140:143], v[194:197], v[40:43]
	v_mfma_f32_16x16x32_bf16 v[28:31], v[132:135], v[202:205], v[28:31]
	v_mfma_f32_16x16x32_bf16 v[24:27], v[140:143], v[202:205], v[24:27]
	v_mfma_f32_16x16x32_bf16 v[12:15], v[132:135], v[210:213], v[12:15]
	v_mfma_f32_16x16x32_bf16 v[8:11], v[140:143], v[210:213], v[8:11]
	s_setprio 0
	s_setprio 1
	v_mfma_f32_16x16x32_bf16 v[52:55], v[160:163], v[182:185], v[52:55]
	v_mfma_f32_16x16x32_bf16 v[48:51], v[174:177], v[182:185], v[48:51]
	v_mfma_f32_16x16x32_bf16 v[36:39], v[160:163], v[190:193], v[36:39]
	v_mfma_f32_16x16x32_bf16 v[32:35], v[174:177], v[190:193], v[32:35]
	v_mfma_f32_16x16x32_bf16 v[20:23], v[160:163], v[198:201], v[20:23]
	v_mfma_f32_16x16x32_bf16 v[16:19], v[174:177], v[198:201], v[16:19]
	v_mfma_f32_16x16x32_bf16 v[4:7], v[160:163], v[206:209], v[4:7]
	v_mfma_f32_16x16x32_bf16 v[0:3], v[174:177], v[206:209], v[0:3]
	v_mfma_f32_16x16x32_bf16 v[52:55], v[170:173], v[186:189], v[52:55]
	v_mfma_f32_16x16x32_bf16 v[48:51], v[178:181], v[186:189], v[48:51]
	v_mfma_f32_16x16x32_bf16 v[36:39], v[170:173], v[194:197], v[36:39]
	v_mfma_f32_16x16x32_bf16 v[32:35], v[178:181], v[194:197], v[32:35]
	v_mfma_f32_16x16x32_bf16 v[20:23], v[170:173], v[202:205], v[20:23]
	v_mfma_f32_16x16x32_bf16 v[16:19], v[178:181], v[202:205], v[16:19]
	v_mfma_f32_16x16x32_bf16 v[4:7], v[170:173], v[210:213], v[4:7]
	v_mfma_f32_16x16x32_bf16 v[0:3], v[178:181], v[210:213], v[0:3]
	s_setprio 0
	s_barrier
	s_add_i32 s77, 0, 0x18000
	s_add_i32 s78, 0, 0x1c000
	v_add_u32_e32 v140, s77, v166
	v_add_u32_e32 v178, s78, v166
	ds_read_b128 v[128:131], v140
	ds_read_b128 v[132:135], v140 offset:1024
	ds_read_b128 v[136:139], v140 offset:2048
	ds_read_b128 v[140:143], v140 offset:3072
	ds_read_b128 v[160:163], v178
	ds_read_b128 v[170:173], v178 offset:1024
	ds_read_b128 v[174:177], v178 offset:2048
	ds_read_b128 v[178:181], v178 offset:3072
	s_add_u32 s28, s42, 0x2000
	s_addc_u32 s29, s43, 0
	s_mov_b32 m0, s46
	ds_read_b128 v[182:185], v169 offset:32768
	ds_read_b128 v[186:189], v169 offset:33792
	ds_read_b128 v[190:193], v169 offset:34816
	ds_read_b128 v[194:197], v169 offset:35840
	ds_read_b128 v[198:201], v169 offset:36864
	ds_read_b128 v[202:205], v169 offset:37888
	ds_read_b128 v[206:209], v169 offset:38912
	ds_read_b128 v[210:213], v169 offset:39936
	global_load_lds_dwordx4 v150, s[28:29]
	s_mov_b32 m0, s47
	s_nop 0
	global_load_lds_dwordx4 v146, s[28:29]
	s_waitcnt vmcnt(8)
	s_waitcnt lgkmcnt(0)
	s_barrier
	s_setprio 1
	s_waitcnt lgkmcnt(0)
	v_mfma_f32_16x16x32_bf16 v[124:127], v[128:131], v[182:185], v[124:127]
	v_mfma_f32_16x16x32_bf16 v[120:123], v[136:139], v[182:185], v[120:123]
	v_mfma_f32_16x16x32_bf16 v[116:119], v[128:131], v[190:193], v[116:119]
	v_mfma_f32_16x16x32_bf16 v[112:115], v[136:139], v[190:193], v[112:115]
	v_mfma_f32_16x16x32_bf16 v[92:95], v[128:131], v[198:201], v[92:95]
	v_mfma_f32_16x16x32_bf16 v[88:91], v[136:139], v[198:201], v[88:91]
	v_mfma_f32_16x16x32_bf16 v[76:79], v[128:131], v[206:209], v[76:79]
	v_mfma_f32_16x16x32_bf16 v[72:75], v[136:139], v[206:209], v[72:75]
	v_mfma_f32_16x16x32_bf16 v[124:127], v[132:135], v[186:189], v[124:127]
	v_mfma_f32_16x16x32_bf16 v[120:123], v[140:143], v[186:189], v[120:123]
	v_mfma_f32_16x16x32_bf16 v[116:119], v[132:135], v[194:197], v[116:119]
	v_mfma_f32_16x16x32_bf16 v[112:115], v[140:143], v[194:197], v[112:115]
	v_mfma_f32_16x16x32_bf16 v[92:95], v[132:135], v[202:205], v[92:95]
	v_mfma_f32_16x16x32_bf16 v[88:91], v[140:143], v[202:205], v[88:91]
	v_mfma_f32_16x16x32_bf16 v[76:79], v[132:135], v[210:213], v[76:79]
	v_mfma_f32_16x16x32_bf16 v[72:75], v[140:143], v[210:213], v[72:75]
	s_setprio 0
	s_setprio 1
	v_mfma_f32_16x16x32_bf16 v[108:111], v[160:163], v[182:185], v[108:111]
	v_mfma_f32_16x16x32_bf16 v[104:107], v[174:177], v[182:185], v[104:107]
	v_mfma_f32_16x16x32_bf16 v[100:103], v[160:163], v[190:193], v[100:103]
	v_mfma_f32_16x16x32_bf16 v[96:99], v[174:177], v[190:193], v[96:99]
	v_mfma_f32_16x16x32_bf16 v[84:87], v[160:163], v[198:201], v[84:87]
	v_mfma_f32_16x16x32_bf16 v[80:83], v[174:177], v[198:201], v[80:83]
	v_mfma_f32_16x16x32_bf16 v[68:71], v[160:163], v[206:209], v[68:71]
	v_mfma_f32_16x16x32_bf16 v[64:67], v[174:177], v[206:209], v[64:67]
	v_mfma_f32_16x16x32_bf16 v[108:111], v[170:173], v[186:189], v[108:111]
	v_mfma_f32_16x16x32_bf16 v[104:107], v[178:181], v[186:189], v[104:107]
	v_mfma_f32_16x16x32_bf16 v[100:103], v[170:173], v[194:197], v[100:103]
	v_mfma_f32_16x16x32_bf16 v[96:99], v[178:181], v[194:197], v[96:99]
	v_mfma_f32_16x16x32_bf16 v[84:87], v[170:173], v[202:205], v[84:87]
	v_mfma_f32_16x16x32_bf16 v[80:83], v[178:181], v[202:205], v[80:83]
	v_mfma_f32_16x16x32_bf16 v[68:71], v[170:173], v[210:213], v[68:71]
	v_mfma_f32_16x16x32_bf16 v[64:67], v[178:181], v[210:213], v[64:67]
	s_setprio 0
	s_barrier
	s_add_u32 s98, s40, s12
	s_addc_u32 s99, s41, s13
	s_add_i32 s28, s77, s35
	s_mov_b32 m0, s28
	ds_read_b128 v[182:185], v169 offset:49152
	ds_read_b128 v[186:189], v169 offset:50176
	ds_read_b128 v[190:193], v169 offset:51200
	ds_read_b128 v[194:197], v169 offset:52224
	ds_read_b128 v[198:201], v169 offset:53248
	ds_read_b128 v[202:205], v169 offset:54272
	ds_read_b128 v[206:209], v169 offset:55296
	ds_read_b128 v[210:213], v169 offset:56320
	global_load_lds_dwordx4 v148, s[98:99]
	s_add_i32 m0, s28, 0x2000
	s_add_u32 s28, s40, 0x40080
	s_addc_u32 s29, s41, 0
	s_add_i32 s40, s78, s35
	global_load_lds_dwordx4 v144, s[98:99]
	s_mov_b32 m0, s40
	s_nop 0
	global_load_lds_dwordx4 v148, s[28:29]
	s_add_i32 m0, s40, 0x2000
	s_nop 0
	global_load_lds_dwordx4 v144, s[28:29]
	s_mov_b32 m0, s68
	s_nop 0
	global_load_lds_dwordx4 v150, s[38:39]
	s_mov_b32 m0, s69
	s_nop 0
	global_load_lds_dwordx4 v146, s[38:39]
	s_waitcnt vmcnt(8)
	s_waitcnt lgkmcnt(0)
	s_barrier
	s_setprio 1
	s_waitcnt lgkmcnt(0)
	v_mfma_f32_16x16x32_bf16 v[60:63], v[128:131], v[182:185], v[60:63]
	v_mfma_f32_16x16x32_bf16 v[56:59], v[136:139], v[182:185], v[56:59]
	v_mfma_f32_16x16x32_bf16 v[44:47], v[128:131], v[190:193], v[44:47]
	v_mfma_f32_16x16x32_bf16 v[40:43], v[136:139], v[190:193], v[40:43]
	v_mfma_f32_16x16x32_bf16 v[28:31], v[128:131], v[198:201], v[28:31]
	v_mfma_f32_16x16x32_bf16 v[24:27], v[136:139], v[198:201], v[24:27]
	v_mfma_f32_16x16x32_bf16 v[12:15], v[128:131], v[206:209], v[12:15]
	v_mfma_f32_16x16x32_bf16 v[8:11], v[136:139], v[206:209], v[8:11]
	v_mfma_f32_16x16x32_bf16 v[60:63], v[132:135], v[186:189], v[60:63]
	v_mfma_f32_16x16x32_bf16 v[56:59], v[140:143], v[186:189], v[56:59]
	v_mfma_f32_16x16x32_bf16 v[44:47], v[132:135], v[194:197], v[44:47]
	v_mfma_f32_16x16x32_bf16 v[40:43], v[140:143], v[194:197], v[40:43]
	v_mfma_f32_16x16x32_bf16 v[28:31], v[132:135], v[202:205], v[28:31]
	v_mfma_f32_16x16x32_bf16 v[24:27], v[140:143], v[202:205], v[24:27]
	v_mfma_f32_16x16x32_bf16 v[12:15], v[132:135], v[210:213], v[12:15]
	v_mfma_f32_16x16x32_bf16 v[8:11], v[140:143], v[210:213], v[8:11]
	s_setprio 0
	s_setprio 1
	v_mfma_f32_16x16x32_bf16 v[52:55], v[160:163], v[182:185], v[52:55]
	v_mfma_f32_16x16x32_bf16 v[48:51], v[174:177], v[182:185], v[48:51]
	v_mfma_f32_16x16x32_bf16 v[36:39], v[160:163], v[190:193], v[36:39]
	v_mfma_f32_16x16x32_bf16 v[32:35], v[174:177], v[190:193], v[32:35]
	v_mfma_f32_16x16x32_bf16 v[20:23], v[160:163], v[198:201], v[20:23]
	v_mfma_f32_16x16x32_bf16 v[16:19], v[174:177], v[198:201], v[16:19]
	v_mfma_f32_16x16x32_bf16 v[4:7], v[160:163], v[206:209], v[4:7]
	v_mfma_f32_16x16x32_bf16 v[0:3], v[174:177], v[206:209], v[0:3]
	v_mfma_f32_16x16x32_bf16 v[52:55], v[170:173], v[186:189], v[52:55]
	v_mfma_f32_16x16x32_bf16 v[48:51], v[178:181], v[186:189], v[48:51]
	v_mfma_f32_16x16x32_bf16 v[36:39], v[170:173], v[194:197], v[36:39]
	v_mfma_f32_16x16x32_bf16 v[32:35], v[178:181], v[194:197], v[32:35]
	v_mfma_f32_16x16x32_bf16 v[20:23], v[170:173], v[202:205], v[20:23]
	v_mfma_f32_16x16x32_bf16 v[16:19], v[178:181], v[202:205], v[16:19]
	v_mfma_f32_16x16x32_bf16 v[4:7], v[170:173], v[210:213], v[4:7]
	v_mfma_f32_16x16x32_bf16 v[0:3], v[178:181], v[210:213], v[0:3]
	s_setprio 0
	s_barrier
	s_add_i32 s76, s76, 2
	s_add_u32 s74, s74, 0x100
	s_addc_u32 s75, s75, 0
	s_cmp_gt_u32 s76, 13
	s_mov_b64 s[28:29], s[36:37]
	s_cbranch_scc0 .LBB0_568
	s_and_b64 vcc, exec, s[10:11]
	s_cbranch_vccz .LBB0_571
	s_barrier

.LBB0_615:
	v_add_u32_e32 v151, s51, v149
	ds_read_b128 v[152:155], v151
	ds_read_b128 v[156:159], v151 offset:1024
	ds_read_b128 v[160:163], v151 offset:2048
	ds_read_b128 v[164:167], v151 offset:3072
	v_add_u32_e32 v151, s56, v149
	ds_read_b128 v[168:171], v151
	ds_read_b128 v[172:175], v151 offset:1024
	ds_read_b128 v[176:179], v151 offset:2048
	ds_read_b128 v[180:183], v151 offset:3072
	s_add_u32 s38, s12, s36
	s_addc_u32 s39, s13, s37
	s_cmp_eq_u32 s63, 60
	s_cselect_b32 s42, s59, s38
	s_cselect_b32 s43, s23, s39
	s_cselect_b32 s40, s60, s61
	s_cselect_b32 s41, s21, s62
	s_add_u32 s38, s42, 0x8000
	s_addc_u32 s39, s43, 0
	s_add_i32 m0, s44, 0xc000
	ds_read_b128 v[184:187], v150
	ds_read_b128 v[188:191], v150 offset:1024
	ds_read_b128 v[192:195], v150 offset:2048
	ds_read_b128 v[196:199], v150 offset:3072
	ds_read_b128 v[200:203], v150 offset:4096
	ds_read_b128 v[204:207], v150 offset:5120
	ds_read_b128 v[208:211], v150 offset:6144
	ds_read_b128 v[212:215], v150 offset:7168
	global_load_lds_dwordx4 v146, s[12:13]
	s_add_i32 m0, s44, 0xe000
	s_nop 0
	global_load_lds_dwordx4 v144, s[12:13]
	s_waitcnt vmcnt(8)
	s_waitcnt lgkmcnt(0)
	s_barrier
	s_setprio 1
	s_waitcnt lgkmcnt(0)
	v_mfma_f32_16x16x32_bf16 v[124:127], v[152:155], v[184:187], v[124:127]
	v_mfma_f32_16x16x32_bf16 v[120:123], v[160:163], v[184:187], v[120:123]
	v_mfma_f32_16x16x32_bf16 v[108:111], v[152:155], v[192:195], v[108:111]
	v_mfma_f32_16x16x32_bf16 v[104:107], v[160:163], v[192:195], v[104:107]
	v_mfma_f32_16x16x32_bf16 v[92:95], v[152:155], v[200:203], v[92:95]
	v_mfma_f32_16x16x32_bf16 v[88:91], v[160:163], v[200:203], v[88:91]
	v_mfma_f32_16x16x32_bf16 v[76:79], v[152:155], v[208:211], v[76:79]
	v_mfma_f32_16x16x32_bf16 v[72:75], v[160:163], v[208:211], v[72:75]
	v_mfma_f32_16x16x32_bf16 v[124:127], v[156:159], v[188:191], v[124:127]
	v_mfma_f32_16x16x32_bf16 v[120:123], v[164:167], v[188:191], v[120:123]
	v_mfma_f32_16x16x32_bf16 v[108:111], v[156:159], v[196:199], v[108:111]
	v_mfma_f32_16x16x32_bf16 v[104:107], v[164:167], v[196:199], v[104:107]
	v_mfma_f32_16x16x32_bf16 v[92:95], v[156:159], v[204:207], v[92:95]
	v_mfma_f32_16x16x32_bf16 v[88:91], v[164:167], v[204:207], v[88:91]
	v_mfma_f32_16x16x32_bf16 v[76:79], v[156:159], v[212:215], v[76:79]
	v_mfma_f32_16x16x32_bf16 v[72:75], v[164:167], v[212:215], v[72:75]
	s_setprio 0
	s_setprio 1
	v_mfma_f32_16x16x32_bf16 v[116:119], v[168:171], v[184:187], v[116:119]
	v_mfma_f32_16x16x32_bf16 v[112:115], v[176:179], v[184:187], v[112:115]
	v_mfma_f32_16x16x32_bf16 v[100:103], v[168:171], v[192:195], v[100:103]
	v_mfma_f32_16x16x32_bf16 v[96:99], v[176:179], v[192:195], v[96:99]
	v_mfma_f32_16x16x32_bf16 v[84:87], v[168:171], v[200:203], v[84:87]
	v_mfma_f32_16x16x32_bf16 v[80:83], v[176:179], v[200:203], v[80:83]
	v_mfma_f32_16x16x32_bf16 v[68:71], v[168:171], v[208:211], v[68:71]
	v_mfma_f32_16x16x32_bf16 v[64:67], v[176:179], v[208:211], v[64:67]
	v_mfma_f32_16x16x32_bf16 v[116:119], v[172:175], v[188:191], v[116:119]
	v_mfma_f32_16x16x32_bf16 v[112:115], v[180:183], v[188:191], v[112:115]
	v_mfma_f32_16x16x32_bf16 v[100:103], v[172:175], v[196:199], v[100:103]
	v_mfma_f32_16x16x32_bf16 v[96:99], v[180:183], v[196:199], v[96:99]
	v_mfma_f32_16x16x32_bf16 v[84:87], v[172:175], v[204:207], v[84:87]
	v_mfma_f32_16x16x32_bf16 v[80:83], v[180:183], v[204:207], v[80:83]
	v_mfma_f32_16x16x32_bf16 v[68:71], v[172:175], v[212:215], v[68:71]
	v_mfma_f32_16x16x32_bf16 v[64:67], v[180:183], v[212:215], v[64:67]
	s_setprio 0
	s_barrier
	s_add_i32 s64, s51, s35
	s_mov_b32 m0, s64
	ds_read_b128 v[184:187], v150 offset:16384
	ds_read_b128 v[188:191], v150 offset:17408
	ds_read_b128 v[192:195], v150 offset:18432
	ds_read_b128 v[196:199], v150 offset:19456
	ds_read_b128 v[200:203], v150 offset:20480
	ds_read_b128 v[204:207], v150 offset:21504
	ds_read_b128 v[208:211], v150 offset:22528
	ds_read_b128 v[212:215], v150 offset:23552
	global_load_lds_dwordx4 v130, s[40:41]
	s_add_i32 m0, s64, 0x2000
	s_add_u32 s64, s40, 0x100000
	v_lshl_add_u64 v[218:219], s[40:41], 0, v[134:135]
	s_addc_u32 s65, s41, 0
	s_add_i32 s66, s56, s35
	global_load_lds_dwordx4 v[218:219], off
	s_mov_b32 m0, s66
	s_nop 0
	global_load_lds_dwordx4 v130, s[64:65]
	s_add_i32 m0, s66, 0x2000
	s_nop 0
	global_load_lds_dwordx4 v134, s[64:65]
	s_mov_b32 m0, s44
	s_nop 0
	global_load_lds_dwordx4 v128, s[42:43]
	s_mov_b32 m0, s45
	s_nop 0
	global_load_lds_dwordx4 v132, s[42:43]
	s_waitcnt vmcnt(8)
	s_waitcnt lgkmcnt(0)
	s_barrier
	s_setprio 1
	s_waitcnt lgkmcnt(0)
	v_mfma_f32_16x16x32_bf16 v[60:63], v[152:155], v[184:187], v[60:63]
	v_mfma_f32_16x16x32_bf16 v[56:59], v[160:163], v[184:187], v[56:59]
	v_mfma_f32_16x16x32_bf16 v[44:47], v[152:155], v[192:195], v[44:47]
	v_mfma_f32_16x16x32_bf16 v[40:43], v[160:163], v[192:195], v[40:43]
	v_mfma_f32_16x16x32_bf16 v[28:31], v[152:155], v[200:203], v[28:31]
	v_mfma_f32_16x16x32_bf16 v[24:27], v[160:163], v[200:203], v[24:27]
	v_mfma_f32_16x16x32_bf16 v[12:15], v[152:155], v[208:211], v[12:15]
	v_mfma_f32_16x16x32_bf16 v[8:11], v[160:163], v[208:211], v[8:11]
	v_mfma_f32_16x16x32_bf16 v[60:63], v[156:159], v[188:191], v[60:63]
	v_mfma_f32_16x16x32_bf16 v[56:59], v[164:167], v[188:191], v[56:59]
	v_mfma_f32_16x16x32_bf16 v[44:47], v[156:159], v[196:199], v[44:47]
	v_mfma_f32_16x16x32_bf16 v[40:43], v[164:167], v[196:199], v[40:43]
	v_mfma_f32_16x16x32_bf16 v[28:31], v[156:159], v[204:207], v[28:31]
	v_mfma_f32_16x16x32_bf16 v[24:27], v[164:167], v[204:207], v[24:27]
	v_mfma_f32_16x16x32_bf16 v[12:15], v[156:159], v[212:215], v[12:15]
	v_mfma_f32_16x16x32_bf16 v[8:11], v[164:167], v[212:215], v[8:11]
	s_setprio 0
	s_setprio 1
	v_mfma_f32_16x16x32_bf16 v[52:55], v[168:171], v[184:187], v[52:55]
	v_mfma_f32_16x16x32_bf16 v[48:51], v[176:179], v[184:187], v[48:51]
	v_mfma_f32_16x16x32_bf16 v[36:39], v[168:171], v[192:195], v[36:39]
	v_mfma_f32_16x16x32_bf16 v[32:35], v[176:179], v[192:195], v[32:35]
	v_mfma_f32_16x16x32_bf16 v[20:23], v[168:171], v[200:203], v[20:23]
	v_mfma_f32_16x16x32_bf16 v[16:19], v[176:179], v[200:203], v[16:19]
	v_mfma_f32_16x16x32_bf16 v[4:7], v[168:171], v[208:211], v[4:7]
	v_mfma_f32_16x16x32_bf16 v[0:3], v[176:179], v[208:211], v[0:3]
	v_mfma_f32_16x16x32_bf16 v[52:55], v[172:175], v[188:191], v[52:55]
	v_mfma_f32_16x16x32_bf16 v[48:51], v[180:183], v[188:191], v[48:51]
	v_mfma_f32_16x16x32_bf16 v[36:39], v[172:175], v[196:199], v[36:39]
	v_mfma_f32_16x16x32_bf16 v[32:35], v[180:183], v[196:199], v[32:35]
	v_mfma_f32_16x16x32_bf16 v[20:23], v[172:175], v[204:207], v[20:23]
	v_mfma_f32_16x16x32_bf16 v[16:19], v[180:183], v[204:207], v[16:19]
	v_mfma_f32_16x16x32_bf16 v[4:7], v[172:175], v[212:215], v[4:7]
	v_mfma_f32_16x16x32_bf16 v[0:3], v[180:183], v[212:215], v[0:3]
	s_setprio 0
	s_barrier
	s_add_i32 s64, 0, 0x18000
	v_add_u32_e32 v151, s64, v149
	s_add_i32 s65, 0, 0x1c000
	ds_read_b128 v[152:155], v151
	ds_read_b128 v[156:159], v151 offset:1024
	ds_read_b128 v[160:163], v151 offset:2048
	ds_read_b128 v[164:167], v151 offset:3072
	v_add_u32_e32 v151, s65, v149
	ds_read_b128 v[168:171], v151
	ds_read_b128 v[172:175], v151 offset:1024
	ds_read_b128 v[176:179], v151 offset:2048
	ds_read_b128 v[180:183], v151 offset:3072
	s_add_u32 s42, s42, 0x2000
	s_addc_u32 s43, s43, 0
	s_mov_b32 m0, s46
	ds_read_b128 v[184:187], v150 offset:32768
	ds_read_b128 v[188:191], v150 offset:33792
	ds_read_b128 v[192:195], v150 offset:34816
	ds_read_b128 v[196:199], v150 offset:35840
	ds_read_b128 v[200:203], v150 offset:36864
	ds_read_b128 v[204:207], v150 offset:37888
	ds_read_b128 v[208:211], v150 offset:38912
	ds_read_b128 v[212:215], v150 offset:39936
	global_load_lds_dwordx4 v128, s[42:43]
	s_mov_b32 m0, s47
	s_nop 0
	global_load_lds_dwordx4 v132, s[42:43]
	s_waitcnt vmcnt(8)
	s_waitcnt lgkmcnt(0)
	s_barrier
	s_setprio 1
	s_waitcnt lgkmcnt(0)
	v_mfma_f32_16x16x32_bf16 v[124:127], v[152:155], v[184:187], v[124:127]
	v_mfma_f32_16x16x32_bf16 v[120:123], v[160:163], v[184:187], v[120:123]
	v_mfma_f32_16x16x32_bf16 v[108:111], v[152:155], v[192:195], v[108:111]
	v_mfma_f32_16x16x32_bf16 v[104:107], v[160:163], v[192:195], v[104:107]
	v_mfma_f32_16x16x32_bf16 v[92:95], v[152:155], v[200:203], v[92:95]
	v_mfma_f32_16x16x32_bf16 v[88:91], v[160:163], v[200:203], v[88:91]
	v_mfma_f32_16x16x32_bf16 v[76:79], v[152:155], v[208:211], v[76:79]
	v_mfma_f32_16x16x32_bf16 v[72:75], v[160:163], v[208:211], v[72:75]
	v_mfma_f32_16x16x32_bf16 v[124:127], v[156:159], v[188:191], v[124:127]
	v_mfma_f32_16x16x32_bf16 v[120:123], v[164:167], v[188:191], v[120:123]
	v_mfma_f32_16x16x32_bf16 v[108:111], v[156:159], v[196:199], v[108:111]
	v_mfma_f32_16x16x32_bf16 v[104:107], v[164:167], v[196:199], v[104:107]
	v_mfma_f32_16x16x32_bf16 v[92:95], v[156:159], v[204:207], v[92:95]
	v_mfma_f32_16x16x32_bf16 v[88:91], v[164:167], v[204:207], v[88:91]
	v_mfma_f32_16x16x32_bf16 v[76:79], v[156:159], v[212:215], v[76:79]
	v_mfma_f32_16x16x32_bf16 v[72:75], v[164:167], v[212:215], v[72:75]
	s_setprio 0
	s_setprio 1
	v_mfma_f32_16x16x32_bf16 v[116:119], v[168:171], v[184:187], v[116:119]
	v_mfma_f32_16x16x32_bf16 v[112:115], v[176:179], v[184:187], v[112:115]
	v_mfma_f32_16x16x32_bf16 v[100:103], v[168:171], v[192:195], v[100:103]
	v_mfma_f32_16x16x32_bf16 v[96:99], v[176:179], v[192:195], v[96:99]
	v_mfma_f32_16x16x32_bf16 v[84:87], v[168:171], v[200:203], v[84:87]
	v_mfma_f32_16x16x32_bf16 v[80:83], v[176:179], v[200:203], v[80:83]
	v_mfma_f32_16x16x32_bf16 v[68:71], v[168:171], v[208:211], v[68:71]
	v_mfma_f32_16x16x32_bf16 v[64:67], v[176:179], v[208:211], v[64:67]
	v_mfma_f32_16x16x32_bf16 v[116:119], v[172:175], v[188:191], v[116:119]
	v_mfma_f32_16x16x32_bf16 v[112:115], v[180:183], v[188:191], v[112:115]
	v_mfma_f32_16x16x32_bf16 v[100:103], v[172:175], v[196:199], v[100:103]
	v_mfma_f32_16x16x32_bf16 v[96:99], v[180:183], v[196:199], v[96:99]
	v_mfma_f32_16x16x32_bf16 v[84:87], v[172:175], v[204:207], v[84:87]
	v_mfma_f32_16x16x32_bf16 v[80:83], v[180:183], v[204:207], v[80:83]
	v_mfma_f32_16x16x32_bf16 v[68:71], v[172:175], v[212:215], v[68:71]
	v_mfma_f32_16x16x32_bf16 v[64:67], v[180:183], v[212:215], v[64:67]
	s_setprio 0
	s_barrier
	s_add_u32 s98, s40, s16
	s_addc_u32 s99, s41, s17
	s_add_i32 s42, s64, s35
	s_mov_b32 m0, s42
	ds_read_b128 v[184:187], v150 offset:49152
	ds_read_b128 v[188:191], v150 offset:50176
	ds_read_b128 v[192:195], v150 offset:51200
	ds_read_b128 v[196:199], v150 offset:52224
	ds_read_b128 v[200:203], v150 offset:53248
	ds_read_b128 v[204:207], v150 offset:54272
	ds_read_b128 v[208:211], v150 offset:55296
	ds_read_b128 v[212:215], v150 offset:56320
	global_load_lds_dwordx4 v130, s[98:99]
	s_add_i32 m0, s42, 0x2000
	s_add_u32 s40, s40, 0x100080
	v_lshl_add_u64 v[216:217], v[218:219], 0, s[16:17]
	s_addc_u32 s41, s41, 0
	s_add_i32 s42, s65, s35
	global_load_lds_dwordx4 v[216:217], off
	s_mov_b32 m0, s42
	s_nop 0
	global_load_lds_dwordx4 v130, s[40:41]
	s_add_i32 m0, s42, 0x2000
	s_nop 0
	global_load_lds_dwordx4 v134, s[40:41]
	s_mov_b32 m0, s48
	s_nop 0
	global_load_lds_dwordx4 v128, s[38:39]
	s_mov_b32 m0, s49
	s_nop 0
	global_load_lds_dwordx4 v132, s[38:39]
	s_waitcnt vmcnt(8)
	s_waitcnt lgkmcnt(0)
	s_barrier
	s_setprio 1
	s_waitcnt lgkmcnt(0)
	v_mfma_f32_16x16x32_bf16 v[60:63], v[152:155], v[184:187], v[60:63]
	v_mfma_f32_16x16x32_bf16 v[56:59], v[160:163], v[184:187], v[56:59]
	v_mfma_f32_16x16x32_bf16 v[44:47], v[152:155], v[192:195], v[44:47]
	v_mfma_f32_16x16x32_bf16 v[40:43], v[160:163], v[192:195], v[40:43]
	v_mfma_f32_16x16x32_bf16 v[28:31], v[152:155], v[200:203], v[28:31]
	v_mfma_f32_16x16x32_bf16 v[24:27], v[160:163], v[200:203], v[24:27]
	v_mfma_f32_16x16x32_bf16 v[12:15], v[152:155], v[208:211], v[12:15]
	v_mfma_f32_16x16x32_bf16 v[8:11], v[160:163], v[208:211], v[8:11]
	v_mfma_f32_16x16x32_bf16 v[60:63], v[156:159], v[188:191], v[60:63]
	v_mfma_f32_16x16x32_bf16 v[56:59], v[164:167], v[188:191], v[56:59]
	v_mfma_f32_16x16x32_bf16 v[44:47], v[156:159], v[196:199], v[44:47]
	v_mfma_f32_16x16x32_bf16 v[40:43], v[164:167], v[196:199], v[40:43]
	v_mfma_f32_16x16x32_bf16 v[28:31], v[156:159], v[204:207], v[28:31]
	v_mfma_f32_16x16x32_bf16 v[24:27], v[164:167], v[204:207], v[24:27]
	v_mfma_f32_16x16x32_bf16 v[12:15], v[156:159], v[212:215], v[12:15]
	v_mfma_f32_16x16x32_bf16 v[8:11], v[164:167], v[212:215], v[8:11]
	s_setprio 0
	s_setprio 1
	v_mfma_f32_16x16x32_bf16 v[52:55], v[168:171], v[184:187], v[52:55]
	v_mfma_f32_16x16x32_bf16 v[48:51], v[176:179], v[184:187], v[48:51]
	v_mfma_f32_16x16x32_bf16 v[36:39], v[168:171], v[192:195], v[36:39]
	v_mfma_f32_16x16x32_bf16 v[32:35], v[176:179], v[192:195], v[32:35]
	v_mfma_f32_16x16x32_bf16 v[20:23], v[168:171], v[200:203], v[20:23]
	v_mfma_f32_16x16x32_bf16 v[16:19], v[176:179], v[200:203], v[16:19]
	v_mfma_f32_16x16x32_bf16 v[4:7], v[168:171], v[208:211], v[4:7]
	v_mfma_f32_16x16x32_bf16 v[0:3], v[176:179], v[208:211], v[0:3]
	v_mfma_f32_16x16x32_bf16 v[52:55], v[172:175], v[188:191], v[52:55]
	v_mfma_f32_16x16x32_bf16 v[48:51], v[180:183], v[188:191], v[48:51]
	v_mfma_f32_16x16x32_bf16 v[36:39], v[172:175], v[196:199], v[36:39]
	v_mfma_f32_16x16x32_bf16 v[32:35], v[180:183], v[196:199], v[32:35]
	v_mfma_f32_16x16x32_bf16 v[20:23], v[172:175], v[204:207], v[20:23]
	v_mfma_f32_16x16x32_bf16 v[16:19], v[180:183], v[204:207], v[16:19]
	v_mfma_f32_16x16x32_bf16 v[4:7], v[172:175], v[212:215], v[4:7]
	v_mfma_f32_16x16x32_bf16 v[0:3], v[180:183], v[212:215], v[0:3]
	s_setprio 0
	s_barrier
	s_add_i32 s63, s63, 2
	s_add_u32 s61, s61, 0x100
	s_addc_u32 s62, s62, 0
	s_add_u32 s36, s36, 0x10000
	s_addc_u32 s37, s37, 0
	v_lshl_add_u64 v[146:147], v[146:147], 0, s[18:19]
	s_cmp_gt_u32 s63, 61
	v_lshl_add_u64 v[144:145], v[144:145], 0, s[18:19]
	s_cbranch_scc0 .LBB0_615
	s_andn2_b64 vcc, exec, s[4:5]
	s_cbranch_vccnz .LBB0_607
	v_mov_b32_e32 v0, 0
	s_mov_b32 s8, s20
	s_mov_b32 s6, s22
	s_mov_b64 s[10:11], s[28:29]
	s_mov_b64 s[12:13], s[26:27]
	s_mov_b32 s50, s57
	v_mov_b32_e32 v1, v0
	v_mov_b32_e32 v2, v0
	v_mov_b32_e32 v3, v0
	v_mov_b32_e32 v4, v0
	v_mov_b32_e32 v5, v0
	v_mov_b32_e32 v6, v0
	v_mov_b32_e32 v7, v0
	v_mov_b32_e32 v16, v0
	v_mov_b32_e32 v17, v0
	v_mov_b32_e32 v18, v0
	v_mov_b32_e32 v19, v0
	v_mov_b32_e32 v20, v0
	v_mov_b32_e32 v21, v0
	v_mov_b32_e32 v22, v0
	v_mov_b32_e32 v23, v0
	v_mov_b32_e32 v32, v0
	v_mov_b32_e32 v33, v0
	v_mov_b32_e32 v34, v0
	v_mov_b32_e32 v35, v0
	v_mov_b32_e32 v36, v0
	v_mov_b32_e32 v37, v0
	v_mov_b32_e32 v38, v0
	v_mov_b32_e32 v39, v0
	v_mov_b32_e32 v48, v0
	v_mov_b32_e32 v49, v0
	v_mov_b32_e32 v50, v0
	v_mov_b32_e32 v51, v0
	v_mov_b32_e32 v52, v0
	v_mov_b32_e32 v53, v0
	v_mov_b32_e32 v54, v0
	v_mov_b32_e32 v55, v0
	v_mov_b32_e32 v8, v0
	v_mov_b32_e32 v9, v0
	v_mov_b32_e32 v10, v0
	v_mov_b32_e32 v11, v0
	v_mov_b32_e32 v12, v0
	v_mov_b32_e32 v13, v0
	v_mov_b32_e32 v14, v0
	v_mov_b32_e32 v15, v0
	v_mov_b32_e32 v24, v0
	v_mov_b32_e32 v25, v0
	v_mov_b32_e32 v26, v0
	v_mov_b32_e32 v27, v0
	v_mov_b32_e32 v28, v0
	v_mov_b32_e32 v29, v0
	v_mov_b32_e32 v30, v0
	v_mov_b32_e32 v31, v0
	v_mov_b32_e32 v40, v0
	v_mov_b32_e32 v41, v0
	v_mov_b32_e32 v42, v0
	v_mov_b32_e32 v43, v0
	v_mov_b32_e32 v44, v0
	v_mov_b32_e32 v45, v0
	v_mov_b32_e32 v46, v0
	v_mov_b32_e32 v47, v0
	v_mov_b32_e32 v56, v0
	v_mov_b32_e32 v57, v0
	v_mov_b32_e32 v58, v0
	v_mov_b32_e32 v59, v0
	v_mov_b32_e32 v60, v0
	v_mov_b32_e32 v61, v0
	v_mov_b32_e32 v62, v0
	v_mov_b32_e32 v63, v0
	v_mov_b32_e32 v64, v0
	v_mov_b32_e32 v65, v0
	v_mov_b32_e32 v66, v0
	v_mov_b32_e32 v67, v0
	v_mov_b32_e32 v68, v0
	v_mov_b32_e32 v69, v0
	v_mov_b32_e32 v70, v0
	v_mov_b32_e32 v71, v0
	v_mov_b32_e32 v80, v0
	v_mov_b32_e32 v81, v0
	v_mov_b32_e32 v82, v0
	v_mov_b32_e32 v83, v0
	v_mov_b32_e32 v84, v0
	v_mov_b32_e32 v85, v0
	v_mov_b32_e32 v86, v0
	v_mov_b32_e32 v87, v0
	v_mov_b32_e32 v96, v0
	v_mov_b32_e32 v97, v0
	v_mov_b32_e32 v98, v0
	v_mov_b32_e32 v99, v0
	v_mov_b32_e32 v100, v0
	v_mov_b32_e32 v101, v0
	v_mov_b32_e32 v102, v0
	v_mov_b32_e32 v103, v0
	v_mov_b32_e32 v112, v0
	v_mov_b32_e32 v113, v0
	v_mov_b32_e32 v114, v0
	v_mov_b32_e32 v115, v0
	v_mov_b32_e32 v116, v0
	v_mov_b32_e32 v117, v0
	v_mov_b32_e32 v118, v0
	v_mov_b32_e32 v119, v0
	v_mov_b32_e32 v72, v0
	v_mov_b32_e32 v73, v0
	v_mov_b32_e32 v74, v0
	v_mov_b32_e32 v75, v0
	v_mov_b32_e32 v76, v0
	v_mov_b32_e32 v77, v0
	v_mov_b32_e32 v78, v0
	v_mov_b32_e32 v79, v0
	v_mov_b32_e32 v88, v0
	v_mov_b32_e32 v89, v0
	v_mov_b32_e32 v90, v0
	v_mov_b32_e32 v91, v0
	v_mov_b32_e32 v92, v0
	v_mov_b32_e32 v93, v0
	v_mov_b32_e32 v94, v0
	v_mov_b32_e32 v95, v0
	v_mov_b32_e32 v104, v0
	v_mov_b32_e32 v105, v0
	v_mov_b32_e32 v106, v0
	v_mov_b32_e32 v107, v0
	v_mov_b32_e32 v108, v0
	v_mov_b32_e32 v109, v0
	v_mov_b32_e32 v110, v0
	v_mov_b32_e32 v111, v0
	v_mov_b32_e32 v120, v0
	v_mov_b32_e32 v121, v0
	v_mov_b32_e32 v122, v0
	v_mov_b32_e32 v123, v0
	v_mov_b32_e32 v124, v0
	v_mov_b32_e32 v125, v0
	v_mov_b32_e32 v126, v0
	v_mov_b32_e32 v127, v0
	s_branch .LBB0_607
